# epilogue de-serialisation extended: ssq loads hoisted above ALIGN_EPI barrier in P3 QKV and P5 gate epilogues too
# baseline (speedup 1.0000x reference)
; #define PG8_STAGE(bufoff, gbase, voff) do { _Pragma("unroll") for (int _i = 0; _i < 2; ++_i) \
;         __builtin_amdgcn_global_load_lds((const unsigned*)((const char*)(gbase) + (voff)[_i]), (LAS unsigned*)(lds + (bufoff) + ldsw + _i * 8192), 16, 0, 0); } while (0)
; #define PG8_LDA(dst, b, h) do { _Pragma("unroll") for (int m = 0; m < 4; ++m) _Pragma("unroll") for (int k = 0; k < 2; ++k) dst[m][k] = *(const LAS bf16x8*)(lds + PG8_SA(b, h) + aoff + m * 2048 + k * 1024); } while (0)
; #define PG8_LDB(dst, b, h) do { _Pragma("unroll") for (int n = 0; n < 2; ++n) _Pragma("unroll") for (int k = 0; k < 2; ++k) dst[n][k] = *(const LAS bf16x8*)(lds + PG8_SB(b, h) + boff + n * 2048 + k * 1024); } while (0)
; #define PG8_MMA(ai, bj, At, Bt) do { __builtin_amdgcn_s_setprio(1); _Pragma("unroll") for (int m = 0; m < 4; ++m) _Pragma("unroll") for (int n = 0; n < 2; ++n) _Pragma("unroll") for (int k = 0; k < 2; ++k) \
;         acc[ai][bj][m][n] = __builtin_amdgcn_mfma_f32_16x16x32_bf16(Bt[n][k], At[m][k], acc[ai][bj][m][n], 0, 0, 0); __builtin_amdgcn_s_setprio(0); } while (0)
; #define PG8_WAIT_V(n) asm volatile("s_waitcnt vmcnt(" #n ")" ::: "memory")
; #define PG8_WAIT_L(n) asm volatile("s_waitcnt lgkmcnt(" #n ")" ::: "memory")
; #define PG8_BAR __builtin_amdgcn_s_barrier()
; #define PG8_SCHED __builtin_amdgcn_sched_barrier(0)
; __device__ __forceinline__ void gemm_phase(LAS unsigned char* lds, const Gemm g, const StaticOrder S, const Epi E) {
;     ...
;             PG8_LDB(B0, 0, 0); PG8_LDB(B1, 0, 1); PG8_SCHED; PG8_LDA(At, 0, 0); PG8_STAGE(PG8_SA(1, 1), a1 + hstepA, voffA);
;             PG8_WAIT_V(8); PG8_WAIT_L(0); PG8_BAR; PG8_MMA(0, 0, At, B0); PG8_MMA(0, 1, At, B1); PG8_BAR; PG8_SCHED;
;             if (full) PG8_LDA(At, 0, 1); PG8_STAGE(PG8_SB(0, 0), b2, voffB); PG8_STAGE(PG8_SB(0, 1), b2 + hstepB, voffB); PG8_STAGE(PG8_SA(0, 0), a2, voffA);
;             PG8_WAIT_V(8); PG8_WAIT_L(0); PG8_BAR; if (full) { PG8_MMA(1, 0, At, B0); PG8_MMA(1, 1, At, B1); } PG8_BAR; PG8_SCHED;
.LBB0_589:
	ds_read_b128 v[50:53], v174
	ds_read_b128 v[54:57], v174 offset:1024
	ds_read_b128 v[58:61], v174 offset:2048
	ds_read_b128 v[62:65], v174 offset:3072
	ds_read_b128 v[164:167], v175
	ds_read_b128 v[168:171], v175 offset:1024
	ds_read_b128 v[182:185], v175 offset:2048
	ds_read_b128 v[186:189], v175 offset:3072
	s_add_u32 s47, s48, 0xfffc0080
	s_addc_u32 s50, s49, -1
	s_cmp_eq_u32 s41, 12
	s_cselect_b32 s53, s43, s50
	s_cselect_b32 s52, s42, s47
	s_cselect_b32 s51, s45, s39
	s_cselect_b32 s50, s44, s5
	v_lshl_add_u64 v[224:225], s[48:49], 0, v[158:159]
	s_add_i32 m0, s55, 0xc000
	ds_read_b128 v[190:193], v176
	ds_read_b128 v[194:197], v176 offset:1024
	ds_read_b128 v[200:203], v176 offset:2048
	ds_read_b128 v[204:207], v176 offset:3072
	ds_read_b128 v[208:211], v176 offset:4096
	ds_read_b128 v[212:215], v176 offset:5120
	ds_read_b128 v[216:219], v176 offset:6144
	ds_read_b128 v[220:223], v176 offset:7168
	global_load_lds_dwordx4 v[224:225], off
	v_lshl_add_u64 v[224:225], s[48:49], 0, v[156:157]
	s_add_i32 m0, s55, 0xe000
	s_nop 0
	global_load_lds_dwordx4 v[224:225], off
	s_waitcnt vmcnt(8)
	s_waitcnt lgkmcnt(0)
	s_barrier
	s_setprio 1
	s_waitcnt lgkmcnt(0)
	v_mfma_f32_16x16x32_bf16 v[142:145], v[50:53], v[190:193], v[142:145]
	v_mfma_f32_16x16x32_bf16 v[138:141], v[58:61], v[190:193], v[138:141]
	v_mfma_f32_16x16x32_bf16 v[126:129], v[50:53], v[200:203], v[126:129]
	v_mfma_f32_16x16x32_bf16 v[122:125], v[58:61], v[200:203], v[122:125]
	v_mfma_f32_16x16x32_bf16 v[110:113], v[50:53], v[208:211], v[110:113]
	v_mfma_f32_16x16x32_bf16 v[106:109], v[58:61], v[208:211], v[106:109]
	v_mfma_f32_16x16x32_bf16 v[94:97], v[50:53], v[216:219], v[94:97]
	v_mfma_f32_16x16x32_bf16 v[90:93], v[58:61], v[216:219], v[90:93]
	v_mfma_f32_16x16x32_bf16 v[142:145], v[54:57], v[194:197], v[142:145]
	v_mfma_f32_16x16x32_bf16 v[138:141], v[62:65], v[194:197], v[138:141]
	v_mfma_f32_16x16x32_bf16 v[126:129], v[54:57], v[204:207], v[126:129]
	v_mfma_f32_16x16x32_bf16 v[122:125], v[62:65], v[204:207], v[122:125]
	v_mfma_f32_16x16x32_bf16 v[110:113], v[54:57], v[212:215], v[110:113]
	v_mfma_f32_16x16x32_bf16 v[106:109], v[62:65], v[212:215], v[106:109]
	v_mfma_f32_16x16x32_bf16 v[94:97], v[54:57], v[220:223], v[94:97]
	v_mfma_f32_16x16x32_bf16 v[90:93], v[62:65], v[220:223], v[90:93]
	s_setprio 0
	s_setprio 1
	v_mfma_f32_16x16x32_bf16 v[134:137], v[164:167], v[190:193], v[134:137]
	v_mfma_f32_16x16x32_bf16 v[130:133], v[182:185], v[190:193], v[130:133]
	v_mfma_f32_16x16x32_bf16 v[118:121], v[164:167], v[200:203], v[118:121]
	v_mfma_f32_16x16x32_bf16 v[114:117], v[182:185], v[200:203], v[114:117]
	v_mfma_f32_16x16x32_bf16 v[102:105], v[164:167], v[208:211], v[102:105]
	v_mfma_f32_16x16x32_bf16 v[98:101], v[182:185], v[208:211], v[98:101]
	v_mfma_f32_16x16x32_bf16 v[86:89], v[164:167], v[216:219], v[86:89]
	v_mfma_f32_16x16x32_bf16 v[82:85], v[182:185], v[216:219], v[82:85]
	v_mfma_f32_16x16x32_bf16 v[134:137], v[168:171], v[194:197], v[134:137]
	v_mfma_f32_16x16x32_bf16 v[130:133], v[186:189], v[194:197], v[130:133]
	v_mfma_f32_16x16x32_bf16 v[118:121], v[168:171], v[204:207], v[118:121]
	v_mfma_f32_16x16x32_bf16 v[114:117], v[186:189], v[204:207], v[114:117]
	v_mfma_f32_16x16x32_bf16 v[102:105], v[168:171], v[212:215], v[102:105]
	v_mfma_f32_16x16x32_bf16 v[98:101], v[186:189], v[212:215], v[98:101]
	v_mfma_f32_16x16x32_bf16 v[86:89], v[168:171], v[220:223], v[86:89]
	v_mfma_f32_16x16x32_bf16 v[82:85], v[186:189], v[220:223], v[82:85]
	s_setprio 0
	s_barrier
	s_add_i32 s47, s70, s54
	v_lshl_add_u64 v[224:225], s[50:51], 0, v[148:149]
	s_mov_b32 m0, s47
	ds_read_b128 v[190:193], v176 offset:16384
	ds_read_b128 v[194:197], v176 offset:17408
	ds_read_b128 v[200:203], v176 offset:18432
	ds_read_b128 v[204:207], v176 offset:19456
	ds_read_b128 v[208:211], v176 offset:20480
	ds_read_b128 v[212:215], v176 offset:21504
	ds_read_b128 v[216:219], v176 offset:22528
	ds_read_b128 v[220:223], v176 offset:23552
	global_load_lds_dwordx4 v[224:225], off
	s_add_i32 m0, s47, 0x2000
	s_add_u32 s62, s50, 0x40000
	v_lshl_add_u64 v[226:227], s[50:51], 0, v[152:153]
	s_addc_u32 s63, s51, 0
	s_add_i32 s47, s71, s54
	global_load_lds_dwordx4 v[226:227], off
	v_lshl_add_u64 v[228:229], s[62:63], 0, v[148:149]
	s_mov_b32 m0, s47
	v_lshl_add_u64 v[230:231], s[52:53], 0, v[150:151]
	global_load_lds_dwordx4 v[228:229], off
	v_lshl_add_u64 v[228:229], s[62:63], 0, v[152:153]
	s_add_i32 m0, s47, 0x2000
	s_nop 0
	global_load_lds_dwordx4 v[228:229], off
	v_lshl_add_u64 v[228:229], s[52:53], 0, v[146:147]
	s_mov_b32 m0, s55
	s_nop 0
	global_load_lds_dwordx4 v[228:229], off
	s_mov_b32 m0, s56
	s_nop 0
	global_load_lds_dwordx4 v[230:231], off
	s_waitcnt vmcnt(8)
	s_waitcnt lgkmcnt(0)
	s_barrier
; #define PG8_STAGE(bufoff, gbase, voff) do { _Pragma("unroll") for (int _i = 0; _i < 2; ++_i) \
;         __builtin_amdgcn_global_load_lds((const unsigned*)((const char*)(gbase) + (voff)[_i]), (LAS unsigned*)(lds + (bufoff) + ldsw + _i * 8192), 16, 0, 0); } while (0)
; #define PG8_LDA(dst, b, h) do { _Pragma("unroll") for (int m = 0; m < 4; ++m) _Pragma("unroll") for (int k = 0; k < 2; ++k) dst[m][k] = *(const LAS bf16x8*)(lds + PG8_SA(b, h) + aoff + m * 2048 + k * 1024); } while (0)
; #define PG8_LDB(dst, b, h) do { _Pragma("unroll") for (int n = 0; n < 2; ++n) _Pragma("unroll") for (int k = 0; k < 2; ++k) dst[n][k] = *(const LAS bf16x8*)(lds + PG8_SB(b, h) + boff + n * 2048 + k * 1024); } while (0)
; #define PG8_MMA(ai, bj, At, Bt) do { __builtin_amdgcn_s_setprio(1); _Pragma("unroll") for (int m = 0; m < 4; ++m) _Pragma("unroll") for (int n = 0; n < 2; ++n) _Pragma("unroll") for (int k = 0; k < 2; ++k) \
;         acc[ai][bj][m][n] = __builtin_amdgcn_mfma_f32_16x16x32_bf16(Bt[n][k], At[m][k], acc[ai][bj][m][n], 0, 0, 0); __builtin_amdgcn_s_setprio(0); } while (0)
; #define PG8_WAIT_V(n) asm volatile("s_waitcnt vmcnt(" #n ")" ::: "memory")
; #define PG8_WAIT_L(n) asm volatile("s_waitcnt lgkmcnt(" #n ")" ::: "memory")
; #define PG8_BAR __builtin_amdgcn_s_barrier()
; #define PG8_SCHED __builtin_amdgcn_sched_barrier(0)
; __device__ __forceinline__ void gemm_phase(LAS unsigned char* lds, const Gemm g, const StaticOrder S, const Epi E) {
;     ...
;             PG8_WAIT_V(8); PG8_WAIT_L(0); PG8_BAR; if (full) { PG8_MMA(1, 0, At, B0); PG8_MMA(1, 1, At, B1); } PG8_BAR; PG8_SCHED;
;             PG8_LDB(B0, 1, 0); PG8_LDB(B1, 1, 1); PG8_SCHED; PG8_LDA(At, 1, 0); PG8_STAGE(PG8_SA(0, 1), a2 + hstepA, voffA);
;             PG8_WAIT_V(8); PG8_WAIT_L(0); PG8_BAR; PG8_MMA(0, 0, At, B0); PG8_MMA(0, 1, At, B1); PG8_BAR; PG8_SCHED;
	s_setprio 1
	s_waitcnt lgkmcnt(0)
	v_mfma_f32_16x16x32_bf16 v[78:81], v[50:53], v[190:193], v[78:81]
	v_mfma_f32_16x16x32_bf16 v[74:77], v[58:61], v[190:193], v[74:77]
	v_mfma_f32_16x16x32_bf16 v[46:49], v[50:53], v[200:203], v[46:49]
	v_mfma_f32_16x16x32_bf16 v[42:45], v[58:61], v[200:203], v[42:45]
	v_mfma_f32_16x16x32_bf16 v[30:33], v[50:53], v[208:211], v[30:33]
	v_mfma_f32_16x16x32_bf16 v[26:29], v[58:61], v[208:211], v[26:29]
	v_mfma_f32_16x16x32_bf16 v[14:17], v[50:53], v[216:219], v[14:17]
	v_mfma_f32_16x16x32_bf16 v[10:13], v[58:61], v[216:219], v[10:13]
	v_mfma_f32_16x16x32_bf16 v[78:81], v[54:57], v[194:197], v[78:81]
	v_mfma_f32_16x16x32_bf16 v[74:77], v[62:65], v[194:197], v[74:77]
	v_mfma_f32_16x16x32_bf16 v[46:49], v[54:57], v[204:207], v[46:49]
	v_mfma_f32_16x16x32_bf16 v[42:45], v[62:65], v[204:207], v[42:45]
	v_mfma_f32_16x16x32_bf16 v[30:33], v[54:57], v[212:215], v[30:33]
	v_mfma_f32_16x16x32_bf16 v[26:29], v[62:65], v[212:215], v[26:29]
	v_mfma_f32_16x16x32_bf16 v[14:17], v[54:57], v[220:223], v[14:17]
	v_mfma_f32_16x16x32_bf16 v[10:13], v[62:65], v[220:223], v[10:13]
	s_setprio 0
	s_setprio 1
	v_mfma_f32_16x16x32_bf16 v[38:41], v[164:167], v[200:203], v[38:41]
	v_mfma_f32_16x16x32_bf16 v[34:37], v[182:185], v[200:203], v[34:37]
	v_mfma_f32_16x16x32_bf16 v[22:25], v[164:167], v[208:211], v[22:25]
	v_mfma_f32_16x16x32_bf16 v[18:21], v[182:185], v[208:211], v[18:21]
	v_mfma_f32_16x16x32_bf16 v[6:9], v[164:167], v[216:219], v[6:9]
	v_mfma_f32_16x16x32_bf16 v[2:5], v[182:185], v[216:219], v[2:5]
	v_mfma_f32_16x16x32_bf16 v[50:53], v[164:167], v[190:193], v[70:73]
	v_mfma_f32_16x16x32_bf16 v[54:57], v[182:185], v[190:193], v[66:69]
	v_mfma_f32_16x16x32_bf16 v[38:41], v[168:171], v[204:207], v[38:41]
	v_mfma_f32_16x16x32_bf16 v[34:37], v[186:189], v[204:207], v[34:37]
	v_mfma_f32_16x16x32_bf16 v[22:25], v[168:171], v[212:215], v[22:25]
	v_mfma_f32_16x16x32_bf16 v[18:21], v[186:189], v[212:215], v[18:21]
	v_mfma_f32_16x16x32_bf16 v[6:9], v[168:171], v[220:223], v[6:9]
	v_mfma_f32_16x16x32_bf16 v[2:5], v[186:189], v[220:223], v[2:5]
	v_mfma_f32_16x16x32_bf16 v[50:53], v[168:171], v[194:197], v[50:53]
	v_mfma_f32_16x16x32_bf16 v[54:57], v[186:189], v[194:197], v[54:57]
	s_setprio 0
	s_barrier
	s_add_i32 s47, 0, 0x18000
	s_add_i32 s62, 0, 0x1c000
	v_add_u32_e32 v70, s47, v173
	v_add_u32_e32 v154, s62, v173
	ds_read_b128 v[58:61], v70
	ds_read_b128 v[62:65], v70 offset:1024
	ds_read_b128 v[66:69], v70 offset:2048
	ds_read_b128 v[70:73], v70 offset:3072
	ds_read_b128 v[164:167], v154
	ds_read_b128 v[168:171], v154 offset:1024
	ds_read_b128 v[182:185], v154 offset:2048
	ds_read_b128 v[186:189], v154 offset:3072
	s_add_u32 s52, s52, 0x40000
	s_addc_u32 s53, s53, 0
	s_mov_b32 m0, s57
	v_lshl_add_u64 v[232:233], s[52:53], 0, v[146:147]
	ds_read_b128 v[190:193], v176 offset:32768
	ds_read_b128 v[194:197], v176 offset:33792
	ds_read_b128 v[200:203], v176 offset:34816
	ds_read_b128 v[204:207], v176 offset:35840
	ds_read_b128 v[208:211], v176 offset:36864
	ds_read_b128 v[212:215], v176 offset:37888
	ds_read_b128 v[216:219], v176 offset:38912
	ds_read_b128 v[220:223], v176 offset:39936
	global_load_lds_dwordx4 v[232:233], off
	v_lshl_add_u64 v[232:233], s[52:53], 0, v[150:151]
	s_mov_b32 m0, s58
	s_nop 0
	global_load_lds_dwordx4 v[232:233], off
	s_waitcnt vmcnt(8)
	s_waitcnt lgkmcnt(0)
	s_barrier
	s_setprio 1
	s_waitcnt lgkmcnt(0)
	v_mfma_f32_16x16x32_bf16 v[142:145], v[58:61], v[190:193], v[142:145]
	v_mfma_f32_16x16x32_bf16 v[138:141], v[66:69], v[190:193], v[138:141]
	v_mfma_f32_16x16x32_bf16 v[126:129], v[58:61], v[200:203], v[126:129]
	v_mfma_f32_16x16x32_bf16 v[122:125], v[66:69], v[200:203], v[122:125]
	v_mfma_f32_16x16x32_bf16 v[110:113], v[58:61], v[208:211], v[110:113]
	v_mfma_f32_16x16x32_bf16 v[106:109], v[66:69], v[208:211], v[106:109]
	v_mfma_f32_16x16x32_bf16 v[94:97], v[58:61], v[216:219], v[94:97]
	v_mfma_f32_16x16x32_bf16 v[90:93], v[66:69], v[216:219], v[90:93]
	v_mfma_f32_16x16x32_bf16 v[142:145], v[62:65], v[194:197], v[142:145]
	v_mfma_f32_16x16x32_bf16 v[138:141], v[70:73], v[194:197], v[138:141]
	v_mfma_f32_16x16x32_bf16 v[126:129], v[62:65], v[204:207], v[126:129]
	v_mfma_f32_16x16x32_bf16 v[122:125], v[70:73], v[204:207], v[122:125]
	v_mfma_f32_16x16x32_bf16 v[110:113], v[62:65], v[212:215], v[110:113]
	v_mfma_f32_16x16x32_bf16 v[106:109], v[70:73], v[212:215], v[106:109]
	v_mfma_f32_16x16x32_bf16 v[94:97], v[62:65], v[220:223], v[94:97]
	v_mfma_f32_16x16x32_bf16 v[90:93], v[70:73], v[220:223], v[90:93]
	s_setprio 0
	s_setprio 1
	v_mfma_f32_16x16x32_bf16 v[134:137], v[164:167], v[190:193], v[134:137]
	v_mfma_f32_16x16x32_bf16 v[130:133], v[182:185], v[190:193], v[130:133]
	v_mfma_f32_16x16x32_bf16 v[118:121], v[164:167], v[200:203], v[118:121]
	v_mfma_f32_16x16x32_bf16 v[114:117], v[182:185], v[200:203], v[114:117]
	v_mfma_f32_16x16x32_bf16 v[102:105], v[164:167], v[208:211], v[102:105]
	v_mfma_f32_16x16x32_bf16 v[98:101], v[182:185], v[208:211], v[98:101]
	v_mfma_f32_16x16x32_bf16 v[86:89], v[164:167], v[216:219], v[86:89]
	v_mfma_f32_16x16x32_bf16 v[82:85], v[182:185], v[216:219], v[82:85]
	v_mfma_f32_16x16x32_bf16 v[134:137], v[168:171], v[194:197], v[134:137]
	v_mfma_f32_16x16x32_bf16 v[130:133], v[186:189], v[194:197], v[130:133]
	v_mfma_f32_16x16x32_bf16 v[118:121], v[168:171], v[204:207], v[118:121]
	v_mfma_f32_16x16x32_bf16 v[114:117], v[186:189], v[204:207], v[114:117]
	v_mfma_f32_16x16x32_bf16 v[102:105], v[168:171], v[212:215], v[102:105]
	v_mfma_f32_16x16x32_bf16 v[98:101], v[186:189], v[212:215], v[98:101]
	v_mfma_f32_16x16x32_bf16 v[86:89], v[168:171], v[220:223], v[86:89]
	v_mfma_f32_16x16x32_bf16 v[82:85], v[186:189], v[220:223], v[82:85]
	s_setprio 0
	s_barrier
; #define PG8_STAGE(bufoff, gbase, voff) do { _Pragma("unroll") for (int _i = 0; _i < 2; ++_i) \
;         __builtin_amdgcn_global_load_lds((const unsigned*)((const char*)(gbase) + (voff)[_i]), (LAS unsigned*)(lds + (bufoff) + ldsw + _i * 8192), 16, 0, 0); } while (0)
; #define PG8_LDA(dst, b, h) do { _Pragma("unroll") for (int m = 0; m < 4; ++m) _Pragma("unroll") for (int k = 0; k < 2; ++k) dst[m][k] = *(const LAS bf16x8*)(lds + PG8_SA(b, h) + aoff + m * 2048 + k * 1024); } while (0)
; #define PG8_MMA(ai, bj, At, Bt) do { __builtin_amdgcn_s_setprio(1); _Pragma("unroll") for (int m = 0; m < 4; ++m) _Pragma("unroll") for (int n = 0; n < 2; ++n) _Pragma("unroll") for (int k = 0; k < 2; ++k) \
;         acc[ai][bj][m][n] = __builtin_amdgcn_mfma_f32_16x16x32_bf16(Bt[n][k], At[m][k], acc[ai][bj][m][n], 0, 0, 0); __builtin_amdgcn_s_setprio(0); } while (0)
; #define PG8_WAIT_V(n) asm volatile("s_waitcnt vmcnt(" #n ")" ::: "memory")
; #define PG8_WAIT_L(n) asm volatile("s_waitcnt lgkmcnt(" #n ")" ::: "memory")
; #define PG8_BAR __builtin_amdgcn_s_barrier()
;     __device__ __forceinline__ bool operator()(f32x4 (&acc)[2][2][4][2], const Unit& u, int wr, int wc, int fr, int fq) const {
;     ...
;         if (ssq) { const int hb = (u.half == 2) ? HALF : 0; float t8[8];
; #pragma unroll
;             for (int q = 0; q < 8; ++q) t8[q] = ssq[row0 + hb + (q >> 2) * HALF + (q & 3) * 16];
;     ...
;             const int pn = u.pn; const bool kvm = (mode == M_MEMKV);
;             const bool isq = !kvm && ((pn < 2) || (pn >= 6 && pn < 9) || (pn == 15));
;             const bool nrm = kvm ? (pn == 0) : ((pn >= 6 && pn < 12) || (pn == 15));
;             const bool rot = !kvm && (pn >= 6 && pn < 12);
;             const float* gp = gains + (kvm ? 192 : ((pn == 15) ? 128 : ((pn < 9) ? 0 : 64)));
; __device__ __forceinline__ void gemm_phase(LAS unsigned char* lds, const Gemm g, const StaticOrder S, const Epi E) {
;     ...
;             PG8_WAIT_V(8); PG8_WAIT_L(0); PG8_BAR; PG8_MMA(0, 0, At, B0); PG8_MMA(0, 1, At, B1); PG8_BAR; PG8_SCHED;
;             if (full) PG8_LDA(At, 1, 1); PG8_STAGE(PG8_SB(1, 0), b3, voffB); PG8_STAGE(PG8_SB(1, 1), b3 + hstepB, voffB); PG8_STAGE(PG8_SA(1, 0), a3, voffA);
;             PG8_WAIT_V(8); PG8_WAIT_L(0); PG8_BAR; if (full) { PG8_MMA(1, 0, At, B0); PG8_MMA(1, 1, At, B1); } PG8_BAR; PG8_SCHED;
;         }
;         if (wr == 0) PG8_BAR;
	s_add_i32 s47, s47, s54
	v_lshl_add_u64 v[224:225], v[224:225], 0, s[26:27]
	s_mov_b32 m0, s47
	ds_read_b128 v[190:193], v176 offset:49152
	ds_read_b128 v[194:197], v176 offset:50176
	ds_read_b128 v[200:203], v176 offset:51200
	ds_read_b128 v[204:207], v176 offset:52224
	ds_read_b128 v[208:211], v176 offset:53248
	ds_read_b128 v[212:215], v176 offset:54272
	ds_read_b128 v[216:219], v176 offset:55296
	ds_read_b128 v[220:223], v176 offset:56320
	global_load_lds_dwordx4 v[224:225], off
	s_add_i32 m0, s47, 0x2000
	s_add_u32 s50, s50, 0x40080
	v_lshl_add_u64 v[224:225], v[226:227], 0, s[26:27]
	s_addc_u32 s51, s51, 0
	s_add_i32 s47, s62, s54
	global_load_lds_dwordx4 v[224:225], off
	v_lshl_add_u64 v[224:225], s[50:51], 0, v[148:149]
	s_mov_b32 m0, s47
	s_nop 0
	global_load_lds_dwordx4 v[224:225], off
	v_lshl_add_u64 v[224:225], s[50:51], 0, v[152:153]
	s_add_i32 m0, s47, 0x2000
	s_nop 0
	global_load_lds_dwordx4 v[224:225], off
	v_lshl_add_u64 v[224:225], v[228:229], 0, s[26:27]
	s_mov_b32 m0, s66
	s_nop 0
	global_load_lds_dwordx4 v[224:225], off
	v_lshl_add_u64 v[224:225], v[230:231], 0, s[26:27]
	s_mov_b32 m0, s67
	s_nop 0
	global_load_lds_dwordx4 v[224:225], off
	s_waitcnt vmcnt(8)
	s_waitcnt lgkmcnt(0)
	s_barrier
	s_setprio 1
	s_waitcnt lgkmcnt(0)
	v_mfma_f32_16x16x32_bf16 v[78:81], v[58:61], v[190:193], v[78:81]
	v_mfma_f32_16x16x32_bf16 v[74:77], v[66:69], v[190:193], v[74:77]
	v_mfma_f32_16x16x32_bf16 v[46:49], v[58:61], v[200:203], v[46:49]
	v_mfma_f32_16x16x32_bf16 v[42:45], v[66:69], v[200:203], v[42:45]
	v_mfma_f32_16x16x32_bf16 v[30:33], v[58:61], v[208:211], v[30:33]
	v_mfma_f32_16x16x32_bf16 v[26:29], v[66:69], v[208:211], v[26:29]
	v_mfma_f32_16x16x32_bf16 v[14:17], v[58:61], v[216:219], v[14:17]
	v_mfma_f32_16x16x32_bf16 v[10:13], v[66:69], v[216:219], v[10:13]
	v_mfma_f32_16x16x32_bf16 v[78:81], v[62:65], v[194:197], v[78:81]
	v_mfma_f32_16x16x32_bf16 v[74:77], v[70:73], v[194:197], v[74:77]
	v_mfma_f32_16x16x32_bf16 v[46:49], v[62:65], v[204:207], v[46:49]
	v_mfma_f32_16x16x32_bf16 v[42:45], v[70:73], v[204:207], v[42:45]
	v_mfma_f32_16x16x32_bf16 v[30:33], v[62:65], v[212:215], v[30:33]
	v_mfma_f32_16x16x32_bf16 v[26:29], v[70:73], v[212:215], v[26:29]
	v_mfma_f32_16x16x32_bf16 v[14:17], v[62:65], v[220:223], v[14:17]
	v_mfma_f32_16x16x32_bf16 v[10:13], v[70:73], v[220:223], v[10:13]
	s_setprio 0
	s_setprio 1
	v_mfma_f32_16x16x32_bf16 v[50:53], v[164:167], v[190:193], v[50:53]
	v_mfma_f32_16x16x32_bf16 v[70:73], v[168:171], v[194:197], v[50:53]
	v_mfma_f32_16x16x32_bf16 v[50:53], v[182:185], v[190:193], v[54:57]
	v_mfma_f32_16x16x32_bf16 v[38:41], v[164:167], v[200:203], v[38:41]
	v_mfma_f32_16x16x32_bf16 v[34:37], v[182:185], v[200:203], v[34:37]
	v_mfma_f32_16x16x32_bf16 v[22:25], v[164:167], v[208:211], v[22:25]
	v_mfma_f32_16x16x32_bf16 v[18:21], v[182:185], v[208:211], v[18:21]
	v_mfma_f32_16x16x32_bf16 v[6:9], v[164:167], v[216:219], v[6:9]
	v_mfma_f32_16x16x32_bf16 v[2:5], v[182:185], v[216:219], v[2:5]
	v_mfma_f32_16x16x32_bf16 v[66:69], v[186:189], v[194:197], v[50:53]
	v_mfma_f32_16x16x32_bf16 v[38:41], v[168:171], v[204:207], v[38:41]
	v_mfma_f32_16x16x32_bf16 v[34:37], v[186:189], v[204:207], v[34:37]
	v_mfma_f32_16x16x32_bf16 v[22:25], v[168:171], v[212:215], v[22:25]
	v_mfma_f32_16x16x32_bf16 v[18:21], v[186:189], v[212:215], v[18:21]
	v_mfma_f32_16x16x32_bf16 v[6:9], v[168:171], v[220:223], v[6:9]
	v_mfma_f32_16x16x32_bf16 v[2:5], v[186:189], v[220:223], v[2:5]
	s_setprio 0
	s_barrier
	s_add_i32 s41, s41, 2
	s_add_u32 s5, s5, 0x100
	s_addc_u32 s39, s39, 0
	s_add_u32 s48, s48, 0x100
	s_addc_u32 s49, s49, 0
	s_cmp_gt_u32 s41, 13
	s_cbranch_scc0 .LBB0_589
	v_mov_b32_e32 v189, v172
	v_mov_b32_e32 v188, v1
	s_nop 0
	v_lshlrev_b32_e64 v50, 8, s4
	v_add3_u32 v166, v188, s59, v50
	v_ashrrev_i32_e32 v167, 31, v166
	v_lshl_add_u64 v[50:51], v[166:167], 2, s[12:13]
	global_load_dword v170, v[50:51], off
	global_load_dword v187, v[50:51], off offset:64
	global_load_dword v186, v[50:51], off offset:128
	global_load_dword v185, v[50:51], off offset:192
	global_load_dword v184, v[50:51], off offset:512
	global_load_dword v183, v[50:51], off offset:576
	global_load_dword v182, v[50:51], off offset:640
	global_load_dword v181, v[50:51], off offset:704
	s_and_b64 vcc, exec, s[36:37]
	s_cbranch_vccz .LBB0_592
	s_barrier
.LBB0_592:
	v_cmp_lt_i32_e64 s[48:49], s46, 15
	v_cmp_eq_u32_e64 s[4:5], s46, 15
	s_and_b64 s[48:49], s[48:49], exec
	v_cmp_lt_i32_e64 s[50:51], s46, 9
	s_cbranch_scc1 .LBB0_594
	s_cmp_eq_u32 s46, 15
	s_cselect_b64 s[48:49], -1, 0
	s_cbranch_execz .LBB0_595
	s_branch .LBB0_596

; #define PG8_STAGE(bufoff, gbase, voff) do { _Pragma("unroll") for (int _i = 0; _i < 2; ++_i) \
;         __builtin_amdgcn_global_load_lds((const unsigned*)((const char*)(gbase) + (voff)[_i]), (LAS unsigned*)(lds + (bufoff) + ldsw + _i * 8192), 16, 0, 0); } while (0)
; #define PG8_LDA(dst, b, h) do { _Pragma("unroll") for (int m = 0; m < 4; ++m) _Pragma("unroll") for (int k = 0; k < 2; ++k) dst[m][k] = *(const LAS bf16x8*)(lds + PG8_SA(b, h) + aoff + m * 2048 + k * 1024); } while (0)
; #define PG8_LDB(dst, b, h) do { _Pragma("unroll") for (int n = 0; n < 2; ++n) _Pragma("unroll") for (int k = 0; k < 2; ++k) dst[n][k] = *(const LAS bf16x8*)(lds + PG8_SB(b, h) + boff + n * 2048 + k * 1024); } while (0)
; #define PG8_MMA(ai, bj, At, Bt) do { __builtin_amdgcn_s_setprio(1); _Pragma("unroll") for (int m = 0; m < 4; ++m) _Pragma("unroll") for (int n = 0; n < 2; ++n) _Pragma("unroll") for (int k = 0; k < 2; ++k) \
;         acc[ai][bj][m][n] = __builtin_amdgcn_mfma_f32_16x16x32_bf16(Bt[n][k], At[m][k], acc[ai][bj][m][n], 0, 0, 0); __builtin_amdgcn_s_setprio(0); } while (0)
; #define PG8_WAIT_V(n) asm volatile("s_waitcnt vmcnt(" #n ")" ::: "memory")
; #define PG8_WAIT_L(n) asm volatile("s_waitcnt lgkmcnt(" #n ")" ::: "memory")
; #define PG8_BAR __builtin_amdgcn_s_barrier()
; #define PG8_SCHED __builtin_amdgcn_sched_barrier(0)
; __device__ __forceinline__ void gemm_phase(LAS unsigned char* lds, const Gemm g, const StaticOrder S, const Epi E) {
;     ...
;             PG8_LDB(B0, 0, 0); PG8_LDB(B1, 0, 1); PG8_SCHED; PG8_LDA(At, 0, 0); PG8_STAGE(PG8_SA(1, 1), a1 + hstepA, voffA);
;             PG8_WAIT_V(8); PG8_WAIT_L(0); PG8_BAR; PG8_MMA(0, 0, At, B0); PG8_MMA(0, 1, At, B1); PG8_BAR; PG8_SCHED;
;             if (full) PG8_LDA(At, 0, 1); PG8_STAGE(PG8_SB(0, 0), b2, voffB); PG8_STAGE(PG8_SB(0, 1), b2 + hstepB, voffB); PG8_STAGE(PG8_SA(0, 0), a2, voffA);
;             PG8_WAIT_V(8); PG8_WAIT_L(0); PG8_BAR; if (full) { PG8_MMA(1, 0, At, B0); PG8_MMA(1, 1, At, B1); } PG8_BAR; PG8_SCHED;
.LBB0_870:
	ds_read_b128 v[156:159], v174
	ds_read_b128 v[160:163], v174 offset:1024
	ds_read_b128 v[178:181], v174 offset:2048
	ds_read_b128 v[182:185], v174 offset:3072
	ds_read_b128 v[186:189], v175
	ds_read_b128 v[190:193], v175 offset:1024
	ds_read_b128 v[194:197], v175 offset:2048
	ds_read_b128 v[200:203], v175 offset:3072
	s_add_u32 s46, s44, 0xfffc0080
	s_addc_u32 s47, s45, -1
	s_cmp_eq_u32 s63, 12
	s_cselect_b32 s49, s41, s47
	s_cselect_b32 s48, s40, s46
	s_cselect_b32 s47, s43, s39
	s_cselect_b32 s46, s42, s37
	v_lshl_add_u64 v[148:149], s[44:45], 0, v[142:143]
	s_add_i32 m0, s51, 0xc000
	ds_read_b128 v[204:207], v176
	ds_read_b128 v[208:211], v176 offset:1024
	ds_read_b128 v[212:215], v176 offset:2048
	ds_read_b128 v[216:219], v176 offset:3072
	ds_read_b128 v[220:223], v176 offset:4096
	ds_read_b128 v[224:227], v176 offset:5120
	ds_read_b128 v[228:231], v176 offset:6144
	ds_read_b128 v[232:235], v176 offset:7168
	global_load_lds_dwordx4 v[148:149], off
	v_lshl_add_u64 v[148:149], s[44:45], 0, v[140:141]
	s_add_i32 m0, s51, 0xe000
	s_nop 0
	global_load_lds_dwordx4 v[148:149], off
	s_waitcnt vmcnt(8)
	s_waitcnt lgkmcnt(0)
	s_barrier
	s_setprio 1
	s_waitcnt lgkmcnt(0)
	v_mfma_f32_16x16x32_bf16 v[126:129], v[156:159], v[204:207], v[126:129]
	v_mfma_f32_16x16x32_bf16 v[122:125], v[178:181], v[204:207], v[122:125]
	v_mfma_f32_16x16x32_bf16 v[118:121], v[156:159], v[212:215], v[118:121]
	v_mfma_f32_16x16x32_bf16 v[114:117], v[178:181], v[212:215], v[114:117]
	v_mfma_f32_16x16x32_bf16 v[110:113], v[156:159], v[220:223], v[110:113]
	v_mfma_f32_16x16x32_bf16 v[106:109], v[178:181], v[220:223], v[106:109]
	v_mfma_f32_16x16x32_bf16 v[102:105], v[156:159], v[228:231], v[102:105]
	v_mfma_f32_16x16x32_bf16 v[98:101], v[178:181], v[228:231], v[98:101]
	v_mfma_f32_16x16x32_bf16 v[126:129], v[160:163], v[208:211], v[126:129]
	v_mfma_f32_16x16x32_bf16 v[122:125], v[182:185], v[208:211], v[122:125]
	v_mfma_f32_16x16x32_bf16 v[118:121], v[160:163], v[216:219], v[118:121]
	v_mfma_f32_16x16x32_bf16 v[114:117], v[182:185], v[216:219], v[114:117]
	v_mfma_f32_16x16x32_bf16 v[110:113], v[160:163], v[224:227], v[110:113]
	v_mfma_f32_16x16x32_bf16 v[106:109], v[182:185], v[224:227], v[106:109]
	v_mfma_f32_16x16x32_bf16 v[102:105], v[160:163], v[232:235], v[102:105]
	v_mfma_f32_16x16x32_bf16 v[98:101], v[182:185], v[232:235], v[98:101]
	s_setprio 0
	s_setprio 1
	v_mfma_f32_16x16x32_bf16 v[62:65], v[186:189], v[204:207], v[62:65]
	v_mfma_f32_16x16x32_bf16 v[58:61], v[194:197], v[204:207], v[58:61]
	v_mfma_f32_16x16x32_bf16 v[54:57], v[186:189], v[212:215], v[54:57]
	v_mfma_f32_16x16x32_bf16 v[50:53], v[194:197], v[212:215], v[50:53]
	v_mfma_f32_16x16x32_bf16 v[46:49], v[186:189], v[220:223], v[46:49]
	v_mfma_f32_16x16x32_bf16 v[42:45], v[194:197], v[220:223], v[42:45]
	v_mfma_f32_16x16x32_bf16 v[38:41], v[186:189], v[228:231], v[38:41]
	v_mfma_f32_16x16x32_bf16 v[34:37], v[194:197], v[228:231], v[34:37]
	v_mfma_f32_16x16x32_bf16 v[62:65], v[190:193], v[208:211], v[62:65]
	v_mfma_f32_16x16x32_bf16 v[58:61], v[200:203], v[208:211], v[58:61]
	v_mfma_f32_16x16x32_bf16 v[54:57], v[190:193], v[216:219], v[54:57]
	v_mfma_f32_16x16x32_bf16 v[50:53], v[200:203], v[216:219], v[50:53]
	v_mfma_f32_16x16x32_bf16 v[46:49], v[190:193], v[224:227], v[46:49]
	v_mfma_f32_16x16x32_bf16 v[42:45], v[200:203], v[224:227], v[42:45]
	v_mfma_f32_16x16x32_bf16 v[38:41], v[190:193], v[232:235], v[38:41]
	v_mfma_f32_16x16x32_bf16 v[34:37], v[200:203], v[232:235], v[34:37]
	s_setprio 0
	s_barrier
	s_add_i32 s64, s68, s27
	v_lshl_add_u64 v[148:149], s[46:47], 0, v[134:135]
	s_mov_b32 m0, s64
	ds_read_b128 v[204:207], v176 offset:16384
	ds_read_b128 v[208:211], v176 offset:17408
	ds_read_b128 v[212:215], v176 offset:18432
	ds_read_b128 v[216:219], v176 offset:19456
	ds_read_b128 v[220:223], v176 offset:20480
	ds_read_b128 v[224:227], v176 offset:21504
	ds_read_b128 v[228:231], v176 offset:22528
	ds_read_b128 v[232:235], v176 offset:23552
	global_load_lds_dwordx4 v[148:149], off
	s_add_i32 m0, s64, 0x2000
	s_add_u32 s64, s46, 0x40000
	v_lshl_add_u64 v[152:153], s[46:47], 0, v[130:131]
	s_addc_u32 s65, s47, 0
	s_add_i32 s71, s69, s27
	global_load_lds_dwordx4 v[152:153], off
	v_lshl_add_u64 v[236:237], s[64:65], 0, v[134:135]
	s_mov_b32 m0, s71
	v_lshl_add_u64 v[238:239], s[48:49], 0, v[132:133]
	global_load_lds_dwordx4 v[236:237], off
	v_lshl_add_u64 v[236:237], s[64:65], 0, v[130:131]
	s_add_i32 m0, s71, 0x2000
	s_nop 0
	global_load_lds_dwordx4 v[236:237], off
	v_lshl_add_u64 v[236:237], s[48:49], 0, v[136:137]
	s_mov_b32 m0, s51
	s_nop 0
	global_load_lds_dwordx4 v[236:237], off
	s_mov_b32 m0, s52
	s_nop 0
	global_load_lds_dwordx4 v[238:239], off
	s_waitcnt vmcnt(8)
	s_waitcnt lgkmcnt(0)
	s_barrier
; #define PG8_STAGE(bufoff, gbase, voff) do { _Pragma("unroll") for (int _i = 0; _i < 2; ++_i) \
;         __builtin_amdgcn_global_load_lds((const unsigned*)((const char*)(gbase) + (voff)[_i]), (LAS unsigned*)(lds + (bufoff) + ldsw + _i * 8192), 16, 0, 0); } while (0)
; #define PG8_LDA(dst, b, h) do { _Pragma("unroll") for (int m = 0; m < 4; ++m) _Pragma("unroll") for (int k = 0; k < 2; ++k) dst[m][k] = *(const LAS bf16x8*)(lds + PG8_SA(b, h) + aoff + m * 2048 + k * 1024); } while (0)
; #define PG8_LDB(dst, b, h) do { _Pragma("unroll") for (int n = 0; n < 2; ++n) _Pragma("unroll") for (int k = 0; k < 2; ++k) dst[n][k] = *(const LAS bf16x8*)(lds + PG8_SB(b, h) + boff + n * 2048 + k * 1024); } while (0)
; #define PG8_MMA(ai, bj, At, Bt) do { __builtin_amdgcn_s_setprio(1); _Pragma("unroll") for (int m = 0; m < 4; ++m) _Pragma("unroll") for (int n = 0; n < 2; ++n) _Pragma("unroll") for (int k = 0; k < 2; ++k) \
;         acc[ai][bj][m][n] = __builtin_amdgcn_mfma_f32_16x16x32_bf16(Bt[n][k], At[m][k], acc[ai][bj][m][n], 0, 0, 0); __builtin_amdgcn_s_setprio(0); } while (0)
; #define PG8_WAIT_V(n) asm volatile("s_waitcnt vmcnt(" #n ")" ::: "memory")
; #define PG8_WAIT_L(n) asm volatile("s_waitcnt lgkmcnt(" #n ")" ::: "memory")
; #define PG8_BAR __builtin_amdgcn_s_barrier()
; #define PG8_SCHED __builtin_amdgcn_sched_barrier(0)
; __device__ __forceinline__ void gemm_phase(LAS unsigned char* lds, const Gemm g, const StaticOrder S, const Epi E) {
;     ...
;             PG8_WAIT_V(8); PG8_WAIT_L(0); PG8_BAR; if (full) { PG8_MMA(1, 0, At, B0); PG8_MMA(1, 1, At, B1); } PG8_BAR; PG8_SCHED;
;             PG8_LDB(B0, 1, 0); PG8_LDB(B1, 1, 1); PG8_SCHED; PG8_LDA(At, 1, 0); PG8_STAGE(PG8_SA(0, 1), a2 + hstepA, voffA);
;             PG8_WAIT_V(8); PG8_WAIT_L(0); PG8_BAR; PG8_MMA(0, 0, At, B0); PG8_MMA(0, 1, At, B1); PG8_BAR; PG8_SCHED;
	s_setprio 1
	s_waitcnt lgkmcnt(0)
	v_mfma_f32_16x16x32_bf16 v[94:97], v[156:159], v[204:207], v[94:97]
	v_mfma_f32_16x16x32_bf16 v[90:93], v[178:181], v[204:207], v[90:93]
	v_mfma_f32_16x16x32_bf16 v[86:89], v[156:159], v[212:215], v[86:89]
	v_mfma_f32_16x16x32_bf16 v[82:85], v[178:181], v[212:215], v[82:85]
	v_mfma_f32_16x16x32_bf16 v[78:81], v[156:159], v[220:223], v[78:81]
	v_mfma_f32_16x16x32_bf16 v[74:77], v[178:181], v[220:223], v[74:77]
	v_mfma_f32_16x16x32_bf16 v[70:73], v[156:159], v[228:231], v[70:73]
	v_mfma_f32_16x16x32_bf16 v[66:69], v[178:181], v[228:231], v[66:69]
	v_mfma_f32_16x16x32_bf16 v[94:97], v[160:163], v[208:211], v[94:97]
	v_mfma_f32_16x16x32_bf16 v[90:93], v[182:185], v[208:211], v[90:93]
	v_mfma_f32_16x16x32_bf16 v[86:89], v[160:163], v[216:219], v[86:89]
	v_mfma_f32_16x16x32_bf16 v[82:85], v[182:185], v[216:219], v[82:85]
	v_mfma_f32_16x16x32_bf16 v[78:81], v[160:163], v[224:227], v[78:81]
	v_mfma_f32_16x16x32_bf16 v[74:77], v[182:185], v[224:227], v[74:77]
	v_mfma_f32_16x16x32_bf16 v[70:73], v[160:163], v[232:235], v[70:73]
	v_mfma_f32_16x16x32_bf16 v[66:69], v[182:185], v[232:235], v[66:69]
	s_setprio 0
	s_setprio 1
	v_mfma_f32_16x16x32_bf16 v[30:33], v[186:189], v[204:207], v[30:33]
	v_mfma_f32_16x16x32_bf16 v[26:29], v[194:197], v[204:207], v[26:29]
	v_mfma_f32_16x16x32_bf16 v[22:25], v[186:189], v[212:215], v[22:25]
	v_mfma_f32_16x16x32_bf16 v[18:21], v[194:197], v[212:215], v[18:21]
	v_mfma_f32_16x16x32_bf16 v[14:17], v[186:189], v[220:223], v[14:17]
	v_mfma_f32_16x16x32_bf16 v[10:13], v[194:197], v[220:223], v[10:13]
	v_mfma_f32_16x16x32_bf16 v[6:9], v[186:189], v[228:231], v[6:9]
	v_mfma_f32_16x16x32_bf16 v[2:5], v[194:197], v[228:231], v[2:5]
	v_mfma_f32_16x16x32_bf16 v[30:33], v[190:193], v[208:211], v[30:33]
	v_mfma_f32_16x16x32_bf16 v[26:29], v[200:203], v[208:211], v[26:29]
	v_mfma_f32_16x16x32_bf16 v[22:25], v[190:193], v[216:219], v[22:25]
	v_mfma_f32_16x16x32_bf16 v[18:21], v[200:203], v[216:219], v[18:21]
	v_mfma_f32_16x16x32_bf16 v[14:17], v[190:193], v[224:227], v[14:17]
	v_mfma_f32_16x16x32_bf16 v[10:13], v[200:203], v[224:227], v[10:13]
	v_mfma_f32_16x16x32_bf16 v[6:9], v[190:193], v[232:235], v[6:9]
	v_mfma_f32_16x16x32_bf16 v[2:5], v[200:203], v[232:235], v[2:5]
	s_setprio 0
	s_barrier
	s_add_i32 s64, 0, 0x18000
	v_add_u32_e32 v138, s64, v173
	s_add_i32 s65, 0, 0x1c000
	ds_read_b128 v[156:159], v138
	ds_read_b128 v[160:163], v138 offset:1024
	ds_read_b128 v[178:181], v138 offset:2048
	ds_read_b128 v[182:185], v138 offset:3072
	v_add_u32_e32 v138, s65, v173
	ds_read_b128 v[186:189], v138
	ds_read_b128 v[190:193], v138 offset:1024
	ds_read_b128 v[194:197], v138 offset:2048
	ds_read_b128 v[200:203], v138 offset:3072
	s_add_u32 s48, s48, 0x40000
	s_addc_u32 s49, s49, 0
	s_mov_b32 m0, s53
	v_lshl_add_u64 v[240:241], s[48:49], 0, v[136:137]
	ds_read_b128 v[204:207], v176 offset:32768
	ds_read_b128 v[208:211], v176 offset:33792
	ds_read_b128 v[212:215], v176 offset:34816
	ds_read_b128 v[216:219], v176 offset:35840
	ds_read_b128 v[220:223], v176 offset:36864
	ds_read_b128 v[224:227], v176 offset:37888
	ds_read_b128 v[228:231], v176 offset:38912
	ds_read_b128 v[232:235], v176 offset:39936
	global_load_lds_dwordx4 v[240:241], off
	v_lshl_add_u64 v[240:241], s[48:49], 0, v[132:133]
	s_mov_b32 m0, s54
	s_nop 0
	global_load_lds_dwordx4 v[240:241], off
	s_waitcnt vmcnt(8)
	s_waitcnt lgkmcnt(0)
	s_barrier
	s_setprio 1
	s_waitcnt lgkmcnt(0)
	v_mfma_f32_16x16x32_bf16 v[126:129], v[156:159], v[204:207], v[126:129]
	v_mfma_f32_16x16x32_bf16 v[122:125], v[178:181], v[204:207], v[122:125]
	v_mfma_f32_16x16x32_bf16 v[118:121], v[156:159], v[212:215], v[118:121]
	v_mfma_f32_16x16x32_bf16 v[114:117], v[178:181], v[212:215], v[114:117]
	v_mfma_f32_16x16x32_bf16 v[110:113], v[156:159], v[220:223], v[110:113]
	v_mfma_f32_16x16x32_bf16 v[106:109], v[178:181], v[220:223], v[106:109]
	v_mfma_f32_16x16x32_bf16 v[102:105], v[156:159], v[228:231], v[102:105]
	v_mfma_f32_16x16x32_bf16 v[98:101], v[178:181], v[228:231], v[98:101]
	v_mfma_f32_16x16x32_bf16 v[126:129], v[160:163], v[208:211], v[126:129]
	v_mfma_f32_16x16x32_bf16 v[122:125], v[182:185], v[208:211], v[122:125]
	v_mfma_f32_16x16x32_bf16 v[118:121], v[160:163], v[216:219], v[118:121]
	v_mfma_f32_16x16x32_bf16 v[114:117], v[182:185], v[216:219], v[114:117]
	v_mfma_f32_16x16x32_bf16 v[110:113], v[160:163], v[224:227], v[110:113]
	v_mfma_f32_16x16x32_bf16 v[106:109], v[182:185], v[224:227], v[106:109]
	v_mfma_f32_16x16x32_bf16 v[102:105], v[160:163], v[232:235], v[102:105]
	v_mfma_f32_16x16x32_bf16 v[98:101], v[182:185], v[232:235], v[98:101]
	s_setprio 0
	s_setprio 1
	v_mfma_f32_16x16x32_bf16 v[62:65], v[186:189], v[204:207], v[62:65]
	v_mfma_f32_16x16x32_bf16 v[58:61], v[194:197], v[204:207], v[58:61]
	v_mfma_f32_16x16x32_bf16 v[54:57], v[186:189], v[212:215], v[54:57]
	v_mfma_f32_16x16x32_bf16 v[50:53], v[194:197], v[212:215], v[50:53]
	v_mfma_f32_16x16x32_bf16 v[46:49], v[186:189], v[220:223], v[46:49]
	v_mfma_f32_16x16x32_bf16 v[42:45], v[194:197], v[220:223], v[42:45]
	v_mfma_f32_16x16x32_bf16 v[38:41], v[186:189], v[228:231], v[38:41]
	v_mfma_f32_16x16x32_bf16 v[34:37], v[194:197], v[228:231], v[34:37]
	v_mfma_f32_16x16x32_bf16 v[62:65], v[190:193], v[208:211], v[62:65]
	v_mfma_f32_16x16x32_bf16 v[58:61], v[200:203], v[208:211], v[58:61]
	v_mfma_f32_16x16x32_bf16 v[54:57], v[190:193], v[216:219], v[54:57]
	v_mfma_f32_16x16x32_bf16 v[50:53], v[200:203], v[216:219], v[50:53]
	v_mfma_f32_16x16x32_bf16 v[46:49], v[190:193], v[224:227], v[46:49]
	v_mfma_f32_16x16x32_bf16 v[42:45], v[200:203], v[224:227], v[42:45]
	v_mfma_f32_16x16x32_bf16 v[38:41], v[190:193], v[232:235], v[38:41]
	v_mfma_f32_16x16x32_bf16 v[34:37], v[200:203], v[232:235], v[34:37]
	s_setprio 0
	s_barrier
; #define PG8_STAGE(bufoff, gbase, voff) do { _Pragma("unroll") for (int _i = 0; _i < 2; ++_i) \
;         __builtin_amdgcn_global_load_lds((const unsigned*)((const char*)(gbase) + (voff)[_i]), (LAS unsigned*)(lds + (bufoff) + ldsw + _i * 8192), 16, 0, 0); } while (0)
; #define PG8_LDA(dst, b, h) do { _Pragma("unroll") for (int m = 0; m < 4; ++m) _Pragma("unroll") for (int k = 0; k < 2; ++k) dst[m][k] = *(const LAS bf16x8*)(lds + PG8_SA(b, h) + aoff + m * 2048 + k * 1024); } while (0)
; #define PG8_MMA(ai, bj, At, Bt) do { __builtin_amdgcn_s_setprio(1); _Pragma("unroll") for (int m = 0; m < 4; ++m) _Pragma("unroll") for (int n = 0; n < 2; ++n) _Pragma("unroll") for (int k = 0; k < 2; ++k) \
;         acc[ai][bj][m][n] = __builtin_amdgcn_mfma_f32_16x16x32_bf16(Bt[n][k], At[m][k], acc[ai][bj][m][n], 0, 0, 0); __builtin_amdgcn_s_setprio(0); } while (0)
; #define PG8_WAIT_V(n) asm volatile("s_waitcnt vmcnt(" #n ")" ::: "memory")
; #define PG8_WAIT_L(n) asm volatile("s_waitcnt lgkmcnt(" #n ")" ::: "memory")
; #define PG8_BAR __builtin_amdgcn_s_barrier()
; #define PG8_SCHED __builtin_amdgcn_sched_barrier(0)
;     __device__ __forceinline__ bool operator()(f32x4 (&acc)[2][2][4][2], const Unit& u, int wr, int wc, int fr, int fq) const {
;     ...
;         if (ssq) { const int hb = (u.half == 2) ? HALF : 0; float t8[8];
; #pragma unroll
;             for (int q = 0; q < 8; ++q) t8[q] = ssq[row0 + hb + (q >> 2) * HALF + (q & 3) * 16];
; __device__ __forceinline__ void gemm_phase(LAS unsigned char* lds, const Gemm g, const StaticOrder S, const Epi E) {
;     ...
;             PG8_WAIT_V(8); PG8_WAIT_L(0); PG8_BAR; PG8_MMA(0, 0, At, B0); PG8_MMA(0, 1, At, B1); PG8_BAR; PG8_SCHED;
;             if (full) PG8_LDA(At, 1, 1); PG8_STAGE(PG8_SB(1, 0), b3, voffB); PG8_STAGE(PG8_SB(1, 1), b3 + hstepB, voffB); PG8_STAGE(PG8_SA(1, 0), a3, voffA);
;             PG8_WAIT_V(8); PG8_WAIT_L(0); PG8_BAR; if (full) { PG8_MMA(1, 0, At, B0); PG8_MMA(1, 1, At, B1); } PG8_BAR; PG8_SCHED;
;         }
;         if (wr == 0) PG8_BAR;
	s_add_i32 s48, s64, s27
	v_lshl_add_u64 v[148:149], v[148:149], 0, s[22:23]
	s_mov_b32 m0, s48
	ds_read_b128 v[204:207], v176 offset:49152
	ds_read_b128 v[208:211], v176 offset:50176
	ds_read_b128 v[212:215], v176 offset:51200
	ds_read_b128 v[216:219], v176 offset:52224
	ds_read_b128 v[220:223], v176 offset:53248
	ds_read_b128 v[224:227], v176 offset:54272
	ds_read_b128 v[228:231], v176 offset:55296
	ds_read_b128 v[232:235], v176 offset:56320
	global_load_lds_dwordx4 v[148:149], off
	s_add_i32 m0, s48, 0x2000
	s_add_u32 s46, s46, 0x40080
	v_lshl_add_u64 v[148:149], v[152:153], 0, s[22:23]
	s_addc_u32 s47, s47, 0
	s_add_i32 s48, s65, s27
	global_load_lds_dwordx4 v[148:149], off
	v_lshl_add_u64 v[148:149], s[46:47], 0, v[134:135]
	s_mov_b32 m0, s48
	s_nop 0
	global_load_lds_dwordx4 v[148:149], off
	v_lshl_add_u64 v[148:149], s[46:47], 0, v[130:131]
	s_add_i32 m0, s48, 0x2000
	s_nop 0
	global_load_lds_dwordx4 v[148:149], off
	v_lshl_add_u64 v[148:149], v[236:237], 0, s[22:23]
	s_mov_b32 m0, s57
	s_nop 0
	global_load_lds_dwordx4 v[148:149], off
	v_lshl_add_u64 v[148:149], v[238:239], 0, s[22:23]
	s_mov_b32 m0, s58
	s_nop 0
	global_load_lds_dwordx4 v[148:149], off
	s_waitcnt vmcnt(8)
	s_waitcnt lgkmcnt(0)
	s_barrier
	s_setprio 1
	s_waitcnt lgkmcnt(0)
	v_mfma_f32_16x16x32_bf16 v[94:97], v[156:159], v[204:207], v[94:97]
	v_mfma_f32_16x16x32_bf16 v[90:93], v[178:181], v[204:207], v[90:93]
	v_mfma_f32_16x16x32_bf16 v[86:89], v[156:159], v[212:215], v[86:89]
	v_mfma_f32_16x16x32_bf16 v[82:85], v[178:181], v[212:215], v[82:85]
	v_mfma_f32_16x16x32_bf16 v[78:81], v[156:159], v[220:223], v[78:81]
	v_mfma_f32_16x16x32_bf16 v[74:77], v[178:181], v[220:223], v[74:77]
	v_mfma_f32_16x16x32_bf16 v[70:73], v[156:159], v[228:231], v[70:73]
	v_mfma_f32_16x16x32_bf16 v[66:69], v[178:181], v[228:231], v[66:69]
	v_mfma_f32_16x16x32_bf16 v[94:97], v[160:163], v[208:211], v[94:97]
	v_mfma_f32_16x16x32_bf16 v[90:93], v[182:185], v[208:211], v[90:93]
	v_mfma_f32_16x16x32_bf16 v[86:89], v[160:163], v[216:219], v[86:89]
	v_mfma_f32_16x16x32_bf16 v[82:85], v[182:185], v[216:219], v[82:85]
	v_mfma_f32_16x16x32_bf16 v[78:81], v[160:163], v[224:227], v[78:81]
	v_mfma_f32_16x16x32_bf16 v[74:77], v[182:185], v[224:227], v[74:77]
	v_mfma_f32_16x16x32_bf16 v[70:73], v[160:163], v[232:235], v[70:73]
	v_mfma_f32_16x16x32_bf16 v[66:69], v[182:185], v[232:235], v[66:69]
	s_setprio 0
	s_setprio 1
	v_mfma_f32_16x16x32_bf16 v[30:33], v[186:189], v[204:207], v[30:33]
	v_mfma_f32_16x16x32_bf16 v[26:29], v[194:197], v[204:207], v[26:29]
	v_mfma_f32_16x16x32_bf16 v[22:25], v[186:189], v[212:215], v[22:25]
	v_mfma_f32_16x16x32_bf16 v[18:21], v[194:197], v[212:215], v[18:21]
	v_mfma_f32_16x16x32_bf16 v[14:17], v[186:189], v[220:223], v[14:17]
	v_mfma_f32_16x16x32_bf16 v[10:13], v[194:197], v[220:223], v[10:13]
	v_mfma_f32_16x16x32_bf16 v[6:9], v[186:189], v[228:231], v[6:9]
	v_mfma_f32_16x16x32_bf16 v[2:5], v[194:197], v[228:231], v[2:5]
	v_mfma_f32_16x16x32_bf16 v[30:33], v[190:193], v[208:211], v[30:33]
	v_mfma_f32_16x16x32_bf16 v[26:29], v[200:203], v[208:211], v[26:29]
	v_mfma_f32_16x16x32_bf16 v[22:25], v[190:193], v[216:219], v[22:25]
	v_mfma_f32_16x16x32_bf16 v[18:21], v[200:203], v[216:219], v[18:21]
	v_mfma_f32_16x16x32_bf16 v[14:17], v[190:193], v[224:227], v[14:17]
	v_mfma_f32_16x16x32_bf16 v[10:13], v[200:203], v[224:227], v[10:13]
	v_mfma_f32_16x16x32_bf16 v[6:9], v[190:193], v[232:235], v[6:9]
	v_mfma_f32_16x16x32_bf16 v[2:5], v[200:203], v[232:235], v[2:5]
	s_setprio 0
	s_barrier
	s_add_i32 s63, s63, 2
	s_add_u32 s37, s37, 0x100
	s_addc_u32 s39, s39, 0
	s_add_u32 s44, s44, 0x100
	s_addc_u32 s45, s45, 0
	s_cmp_gt_u32 s63, 13
	s_cbranch_scc0 .LBB0_870
	v_mov_b32_e32 v138, v1
	v_mov_b32_e32 v150, v199
	s_lshl_b32 s16, s16, 8
	s_add_i32 s37, s16, s55
	v_add_u32_e32 v148, s37, v138
	v_ashrrev_i32_e32 v149, 31, v148
	v_lshl_add_u64 v[148:149], v[148:149], 2, s[12:13]
	global_load_dword v154, v[148:149], off
	global_load_dword v162, v[148:149], off offset:64
	global_load_dword v163, v[148:149], off offset:128
	global_load_dword v184, v[148:149], off offset:192
	global_load_dword v185, v[148:149], off offset:512
	global_load_dword v186, v[148:149], off offset:576
	global_load_dword v187, v[148:149], off offset:640
	global_load_dword v188, v[148:149], off offset:704
	s_and_b64 vcc, exec, s[24:25]
	s_cbranch_vccz .LBB0_873
	s_barrier
; __device__ __forceinline__ unsigned cvt_pk_bf16(float lo, float hi) { f32x2 v = {lo, hi}; bf2_t b = __builtin_convertvector(v, bf2_t); return __builtin_bit_cast(unsigned, b); }
; #define SG_(t) fmaxf(__builtin_amdgcn_rcpf(1.f + __builtin_amdgcn_exp2f(t)), 1e-30f)
;     __device__ __forceinline__ bool operator()(f32x4 (&acc)[2][2][4][2], const Unit& u, int wr, int wc, int fr, int fq) const {
;     ...
;             for (int q = 0; q < 8; ++q) ri8[q] = __builtin_amdgcn_rsqf(t8[q] * (1.0f / D) + EPS);
;     ...
;             const int gsub = u.pn >> 2;
; #pragma unroll
;             for (int bj = 0; bj < 2; ++bj) { const int colin = (u.pn & 3) * BM + bj * HALF + wc * 32 + 8 * fq;
;                 const f32x4 nb0 = *(const f32x4*)(bias + gsub * D + colin) * -1.4426950408889634f, nb1 = *(const f32x4*)(bias + gsub * D + colin + 4) * -1.4426950408889634f;
; #pragma unroll
;                 for (int ai = 0; ai < 2; ++ai)
; #pragma unroll
;                     for (int m = 0; m < 4; ++m) { const int row = row0 + ai * HALF + m * 16; const float ri = ri8[4 * ai + m];
;                         const float k2 = ri * -1.4426950408889634f;
;                         const f32x4 a = acc[ai][bj][m][0] * k2 + nb0, b = acc[ai][bj][m][1] * k2 + nb1;
;     ...
;                         u32x4 w; w.x = cvt_pk_bf16(SG_(a[0]), SG_(a[1])); w.y = cvt_pk_bf16(SG_(a[2]), SG_(a[3]));
;                         w.z = cvt_pk_bf16(SG_(b[0]), SG_(b[1])); w.w = cvt_pk_bf16(SG_(b[2]), SG_(b[3]));
;     ...
;                         *(u32x4*)gptr(gsub, u.pm, u.pn & 3, wr * 4 + wc, ai * 8 + m * 2 + bj, fq * 16 + fr) = w; } }
.LBB0_873:
	s_lshl_b32 s37, s62, 8
	s_and_b32 s44, s37, 0xfffffc00
	s_ashr_i32 s45, s44, 31
	s_or_b32 s39, s37, 0x300
	s_cmp_gt_u32 s62, 3
	s_cselect_b32 s46, s39, 0x200
	s_and_b32 s37, s37, 0x300
	s_ashr_i32 s47, s46, 31
	s_or_b32 s39, s37, s56
	s_lshl_b64 s[44:45], s[44:45], 2
	v_lshl_add_u32 v148, v150, 3, s39
	s_add_u32 s44, s14, s44
	s_addc_u32 s45, s15, s45
	v_ashrrev_i32_e32 v149, 31, v148
	v_lshl_add_u64 v[152:153], v[148:149], 2, s[44:45]
	global_load_dwordx4 v[156:159], v[152:153], off
	global_load_dwordx4 v[178:181], v[152:153], off offset:16
	v_lshl_add_u32 v138, v150, 4, v138
	v_ashrrev_i32_e32 v148, 5, v138
	s_add_i32 s39, s16, s66
	v_add_u32_e32 v148, s39, v148
	v_ashrrev_i32_e32 v149, 31, v148
	v_lshlrev_b64 v[160:161], 13, v[148:149]
	s_lshl_b64 s[44:45], s[46:47], 1
	v_lshl_add_u64 v[160:161], s[20:21], 0, v[160:161]
	v_lshl_add_u64 v[182:183], v[160:161], 0, s[44:45]
	s_lshl_b32 s16, s37, 1
	s_andn2_b64 vcc, exec, s[2:3]
	s_mov_b64 s[2:3], -1
	s_waitcnt vmcnt(0)
	v_fmamk_f32 v149, v154, 0x3a800000, v177
	v_fmamk_f32 v150, v162, 0x3a800000, v177
	v_fmamk_f32 v154, v163, 0x3a800000, v177
	v_fmamk_f32 v160, v184, 0x3a800000, v177
	v_fmamk_f32 v161, v185, 0x3a800000, v177
	v_rsq_f32_e32 v185, v149
	v_fmamk_f32 v162, v186, 0x3a800000, v177
	v_fmamk_f32 v163, v187, 0x3a800000, v177
	v_fmamk_f32 v184, v188, 0x3a800000, v177
	v_rsq_f32_e32 v186, v150
	v_rsq_f32_e32 v187, v154
	v_rsq_f32_e32 v188, v160
	v_rsq_f32_e32 v150, v161
	v_pk_mul_f32 v[160:161], v[158:159], s[26:27] op_sel_hi:[1,0]
	v_mul_f32_e32 v154, 0xbfb8aa3b, v185
	v_rsq_f32_e32 v189, v162
	v_rsq_f32_e32 v190, v163
	v_pk_mul_f32 v[162:163], v[156:157], s[26:27] op_sel_hi:[1,0]
	v_pk_mul_f32 v[156:157], v[178:179], s[26:27] op_sel_hi:[1,0]
	v_pk_fma_f32 v[128:129], v[128:129], v[154:155], v[160:161] op_sel_hi:[1,0,1] neg_lo:[0,0,1] neg_hi:[0,0,1]
	v_pk_mul_f32 v[158:159], v[180:181], s[26:27] op_sel_hi:[1,0]
	v_pk_fma_f32 v[126:127], v[126:127], v[154:155], v[162:163] op_sel_hi:[1,0,1] neg_lo:[0,0,1] neg_hi:[0,0,1]
	v_pk_fma_f32 v[122:123], v[122:123], v[154:155], v[156:157] op_sel_hi:[1,0,1] neg_lo:[0,0,1] neg_hi:[0,0,1]
	v_exp_f32_e32 v128, v128
	v_exp_f32_e32 v129, v129
	v_pk_fma_f32 v[124:125], v[124:125], v[154:155], v[158:159] op_sel_hi:[1,0,1] neg_lo:[0,0,1] neg_hi:[0,0,1]
	v_exp_f32_e32 v126, v126
	v_exp_f32_e32 v127, v127
	v_exp_f32_e32 v123, v123
	v_exp_f32_e32 v122, v122
	v_exp_f32_e32 v124, v124
	v_exp_f32_e32 v125, v125
	v_add_f32_e32 v128, 1.0, v128
	v_add_f32_e32 v129, 1.0, v129
	v_add_f32_e32 v126, 1.0, v126
	v_add_f32_e32 v127, 1.0, v127
	v_add_f32_e32 v123, 1.0, v123
	v_rcp_f32_e32 v128, v128
	v_rcp_f32_e32 v129, v129
	v_add_f32_e32 v122, 1.0, v122
	v_add_f32_e32 v124, 1.0, v124
	v_add_f32_e32 v125, 1.0, v125
	v_rcp_f32_e32 v126, v126
	v_rcp_f32_e32 v127, v127
	v_rcp_f32_e32 v123, v123
	v_rcp_f32_e32 v122, v122
	v_rcp_f32_e32 v124, v124
	v_rcp_f32_e32 v125, v125
	v_max_f32_e32 v128, 0xda24260, v128
	v_max_f32_e32 v129, 0xda24260, v129
	v_max_f32_e32 v126, 0xda24260, v126
	v_max_f32_e32 v127, 0xda24260, v127
	v_max_f32_e32 v179, 0xda24260, v123
	v_cvt_pk_bf16_f32 v123, v128, v129
	v_lshlrev_b32_e32 v128, 4, v138
	v_max_f32_e32 v178, 0xda24260, v122
	v_max_f32_e32 v180, 0xda24260, v124
	v_max_f32_e32 v125, 0xda24260, v125
	v_cvt_pk_bf16_f32 v122, v126, v127
	v_lshl_add_u64 v[126:127], v[182:183], 0, s[16:17]
	v_and_b32_e32 v138, 0x1f0, v128
	v_cvt_pk_bf16_f32 v124, v178, v179
	v_cvt_pk_bf16_f32 v125, v180, v125
	v_lshl_add_u64 v[126:127], v[126:127], 0, v[138:139]
	global_store_dwordx4 v[126:127], v[122:125], off
	v_mul_f32_e32 v150, 0xbfb8aa3b, v150
	v_pk_fma_f32 v[94:95], v[94:95], v[150:151], v[162:163] op_sel_hi:[1,0,1] neg_lo:[0,0,1] neg_hi:[0,0,1]
	v_mul_f32_e32 v122, 0xbfb8aa3b, v186
	v_pk_fma_f32 v[118:119], v[118:119], v[122:123], v[162:163] op_sel_hi:[1,0,1] neg_lo:[0,0,1] neg_hi:[0,0,1]
	v_pk_fma_f32 v[120:121], v[120:121], v[122:123], v[160:161] op_sel_hi:[1,0,1] neg_lo:[0,0,1] neg_hi:[0,0,1]
	v_exp_f32_e32 v118, v118
	v_exp_f32_e32 v119, v119
	v_pk_fma_f32 v[116:117], v[116:117], v[122:123], v[158:159] op_sel_hi:[1,0,1] neg_lo:[0,0,1] neg_hi:[0,0,1]
	v_exp_f32_e32 v94, v94
	v_add_f32_e32 v118, 1.0, v118
	v_rcp_f32_e32 v123, v118
	v_add_f32_e32 v118, 1.0, v119
	v_rcp_f32_e32 v124, v118
	v_exp_f32_e32 v116, v116
	v_pk_fma_f32 v[118:119], v[114:115], v[122:123], v[156:157] op_sel_hi:[1,0,1] neg_lo:[0,0,1] neg_hi:[0,0,1]
	v_max_f32_e32 v114, 0xda24260, v123
	v_exp_f32_e32 v115, v120
	v_max_f32_e32 v120, 0xda24260, v124
	v_cvt_pk_bf16_f32 v114, v114, v120
	v_exp_f32_e32 v120, v121
	v_add_f32_e32 v115, 1.0, v115
	v_rcp_f32_e32 v115, v115
	v_exp_f32_e32 v118, v118
	v_add_f32_e32 v120, 1.0, v120
	v_rcp_f32_e32 v120, v120
	v_exp_f32_e32 v119, v119
	v_exp_f32_e32 v117, v117
	v_max_f32_e32 v115, 0xda24260, v115
	v_add_f32_e32 v118, 1.0, v118
	v_max_f32_e32 v120, 0xda24260, v120
	v_add_f32_e32 v119, 1.0, v119
	v_add_f32_e32 v116, 1.0, v116
	v_rcp_f32_e32 v118, v118
	v_cvt_pk_bf16_f32 v115, v115, v120
	v_rcp_f32_e32 v119, v119
	v_rcp_f32_e32 v120, v116
	v_add_f32_e32 v116, 1.0, v117
	v_rcp_f32_e32 v117, v116
	v_max_f32_e32 v118, 0xda24260, v118
	v_max_f32_e32 v116, 0xda24260, v119
	v_cvt_pk_bf16_f32 v116, v118, v116
	v_max_f32_e32 v118, 0xda24260, v120
	v_max_f32_e32 v117, 0xda24260, v117
	v_cvt_pk_bf16_f32 v117, v118, v117
	v_add_u32_e32 v118, 4, v148
	v_ashrrev_i32_e32 v119, 31, v118
	v_lshlrev_b64 v[118:119], 13, v[118:119]
	v_lshl_add_u64 v[118:119], s[20:21], 0, v[118:119]
	v_lshl_add_u64 v[118:119], v[118:119], 0, s[44:45]
	v_lshl_add_u64 v[118:119], v[118:119], 0, s[16:17]
	v_lshl_add_u64 v[118:119], v[118:119], 0, v[138:139]
; __device__ __forceinline__ unsigned cvt_pk_bf16(float lo, float hi) { f32x2 v = {lo, hi}; bf2_t b = __builtin_convertvector(v, bf2_t); return __builtin_bit_cast(unsigned, b); }
; #define SG_(t) fmaxf(__builtin_amdgcn_rcpf(1.f + __builtin_amdgcn_exp2f(t)), 1e-30f)
;     __device__ __forceinline__ bool operator()(f32x4 (&acc)[2][2][4][2], const Unit& u, int wr, int wc, int fr, int fq) const {
;     ...
;                 for (int ai = 0; ai < 2; ++ai)
; #pragma unroll
;                     for (int m = 0; m < 4; ++m) { const int row = row0 + ai * HALF + m * 16; const float ri = ri8[4 * ai + m];
;                         const float k2 = ri * -1.4426950408889634f;
;                         const f32x4 a = acc[ai][bj][m][0] * k2 + nb0, b = acc[ai][bj][m][1] * k2 + nb1;
;     ...
;                         u32x4 w; w.x = cvt_pk_bf16(SG_(a[0]), SG_(a[1])); w.y = cvt_pk_bf16(SG_(a[2]), SG_(a[3]));
;                         w.z = cvt_pk_bf16(SG_(b[0]), SG_(b[1])); w.w = cvt_pk_bf16(SG_(b[2]), SG_(b[3]));
;     ...
;                         *(u32x4*)gptr(gsub, u.pm, u.pn & 3, wr * 4 + wc, ai * 8 + m * 2 + bj, fq * 16 + fr) = w; } }
	global_store_dwordx4 v[118:119], v[114:117], off
	v_exp_f32_e32 v95, v95
	v_add_f32_e32 v94, 1.0, v94
	v_mul_f32_e32 v114, 0xbfb8aa3b, v187
	v_pk_fma_f32 v[110:111], v[110:111], v[114:115], v[162:163] op_sel_hi:[1,0,1] neg_lo:[0,0,1] neg_hi:[0,0,1]
	v_pk_fma_f32 v[112:113], v[112:113], v[114:115], v[160:161] op_sel_hi:[1,0,1] neg_lo:[0,0,1] neg_hi:[0,0,1]
	v_exp_f32_e32 v110, v110
	v_exp_f32_e32 v111, v111
	v_pk_fma_f32 v[108:109], v[108:109], v[114:115], v[158:159] op_sel_hi:[1,0,1] neg_lo:[0,0,1] neg_hi:[0,0,1]
	v_pk_fma_f32 v[96:97], v[96:97], v[150:151], v[160:161] op_sel_hi:[1,0,1] neg_lo:[0,0,1] neg_hi:[0,0,1]
	v_add_f32_e32 v110, 1.0, v110
	v_rcp_f32_e32 v115, v110
	v_add_f32_e32 v110, 1.0, v111
	v_rcp_f32_e32 v116, v110
	v_exp_f32_e32 v108, v108
	v_pk_fma_f32 v[110:111], v[106:107], v[114:115], v[156:157] op_sel_hi:[1,0,1] neg_lo:[0,0,1] neg_hi:[0,0,1]
	v_max_f32_e32 v106, 0xda24260, v115
	v_exp_f32_e32 v107, v112
	v_max_f32_e32 v112, 0xda24260, v116
	v_cvt_pk_bf16_f32 v106, v106, v112
	v_exp_f32_e32 v112, v113
	v_add_f32_e32 v107, 1.0, v107
	v_rcp_f32_e32 v107, v107
	v_exp_f32_e32 v110, v110
	v_add_f32_e32 v112, 1.0, v112
	v_rcp_f32_e32 v112, v112
	v_exp_f32_e32 v111, v111
	v_exp_f32_e32 v109, v109
	v_max_f32_e32 v107, 0xda24260, v107
	v_add_f32_e32 v110, 1.0, v110
	v_max_f32_e32 v112, 0xda24260, v112
	v_add_f32_e32 v111, 1.0, v111
	v_add_f32_e32 v108, 1.0, v108
	v_rcp_f32_e32 v110, v110
	v_cvt_pk_bf16_f32 v107, v107, v112
	v_rcp_f32_e32 v111, v111
	v_rcp_f32_e32 v112, v108
	v_add_f32_e32 v108, 1.0, v109
	v_rcp_f32_e32 v109, v108
	v_max_f32_e32 v110, 0xda24260, v110
	v_max_f32_e32 v108, 0xda24260, v111
	v_cvt_pk_bf16_f32 v108, v110, v108
	v_max_f32_e32 v110, 0xda24260, v112
	v_max_f32_e32 v109, 0xda24260, v109
	v_cvt_pk_bf16_f32 v109, v110, v109
	v_add_u32_e32 v110, 8, v148
	v_ashrrev_i32_e32 v111, 31, v110
	v_lshlrev_b64 v[110:111], 13, v[110:111]
	v_lshl_add_u64 v[110:111], s[20:21], 0, v[110:111]
	v_lshl_add_u64 v[110:111], v[110:111], 0, s[44:45]
	v_lshl_add_u64 v[110:111], v[110:111], 0, s[16:17]
	v_lshl_add_u64 v[110:111], v[110:111], 0, v[138:139]
	global_store_dwordx4 v[110:111], v[106:109], off
	v_pk_fma_f32 v[92:93], v[92:93], v[150:151], v[158:159] op_sel_hi:[1,0,1] neg_lo:[0,0,1] neg_hi:[0,0,1]
	v_rsq_f32_e32 v149, v184
	v_mul_f32_e32 v106, 0xbfb8aa3b, v188
	v_pk_fma_f32 v[102:103], v[102:103], v[106:107], v[162:163] op_sel_hi:[1,0,1] neg_lo:[0,0,1] neg_hi:[0,0,1]
	v_pk_fma_f32 v[104:105], v[104:105], v[106:107], v[160:161] op_sel_hi:[1,0,1] neg_lo:[0,0,1] neg_hi:[0,0,1]
	v_exp_f32_e32 v102, v102
	v_exp_f32_e32 v103, v103
	v_pk_fma_f32 v[100:101], v[100:101], v[106:107], v[158:159] op_sel_hi:[1,0,1] neg_lo:[0,0,1] neg_hi:[0,0,1]
	v_exp_f32_e32 v92, v92
	v_add_f32_e32 v102, 1.0, v102
	v_rcp_f32_e32 v107, v102
	v_add_f32_e32 v102, 1.0, v103
	v_rcp_f32_e32 v108, v102
	v_exp_f32_e32 v100, v100
	v_pk_fma_f32 v[102:103], v[98:99], v[106:107], v[156:157] op_sel_hi:[1,0,1] neg_lo:[0,0,1] neg_hi:[0,0,1]
	v_max_f32_e32 v98, 0xda24260, v107
	v_exp_f32_e32 v99, v104
	v_max_f32_e32 v104, 0xda24260, v108
	v_cvt_pk_bf16_f32 v98, v98, v104
	v_exp_f32_e32 v104, v105
	v_add_f32_e32 v99, 1.0, v99
	v_rcp_f32_e32 v99, v99
	v_exp_f32_e32 v102, v102
	v_add_f32_e32 v104, 1.0, v104
	v_rcp_f32_e32 v104, v104
	v_exp_f32_e32 v103, v103
	v_exp_f32_e32 v101, v101
	v_max_f32_e32 v99, 0xda24260, v99
	v_add_f32_e32 v102, 1.0, v102
	v_max_f32_e32 v104, 0xda24260, v104
	v_add_f32_e32 v103, 1.0, v103
	v_add_f32_e32 v100, 1.0, v100
	v_rcp_f32_e32 v102, v102
	v_cvt_pk_bf16_f32 v99, v99, v104
	v_rcp_f32_e32 v103, v103
	v_rcp_f32_e32 v104, v100
	v_add_f32_e32 v100, 1.0, v101
	v_rcp_f32_e32 v101, v100
	v_max_f32_e32 v102, 0xda24260, v102
	v_max_f32_e32 v100, 0xda24260, v103
	v_cvt_pk_bf16_f32 v100, v102, v100
	v_max_f32_e32 v102, 0xda24260, v104
	v_max_f32_e32 v101, 0xda24260, v101
	v_cvt_pk_bf16_f32 v101, v102, v101
	v_add_u32_e32 v102, 12, v148
	v_ashrrev_i32_e32 v103, 31, v102
	v_lshlrev_b64 v[102:103], 13, v[102:103]
	v_lshl_add_u64 v[102:103], s[20:21], 0, v[102:103]
	v_lshl_add_u64 v[102:103], v[102:103], 0, s[44:45]
	v_lshl_add_u64 v[102:103], v[102:103], 0, s[16:17]
	v_lshl_add_u64 v[102:103], v[102:103], 0, v[138:139]
	global_store_dwordx4 v[102:103], v[98:101], off
	v_exp_f32_e32 v93, v93
	v_add_f32_e32 v92, 1.0, v92
	v_rcp_f32_e32 v98, v94
	v_add_f32_e32 v94, 1.0, v95
	v_rcp_f32_e32 v99, v94
	v_pk_fma_f32 v[94:95], v[90:91], v[150:151], v[156:157] op_sel_hi:[1,0,1] neg_lo:[0,0,1] neg_hi:[0,0,1]
	v_max_f32_e32 v90, 0xda24260, v98
	v_exp_f32_e32 v91, v96
	v_max_f32_e32 v96, 0xda24260, v99
	v_cvt_pk_bf16_f32 v90, v90, v96
	v_exp_f32_e32 v96, v97
	v_add_f32_e32 v91, 1.0, v91
	v_rcp_f32_e32 v91, v91
	v_exp_f32_e32 v94, v94
	v_add_f32_e32 v96, 1.0, v96
	v_rcp_f32_e32 v96, v96
	v_exp_f32_e32 v95, v95
	v_max_f32_e32 v91, 0xda24260, v91
	v_add_f32_e32 v94, 1.0, v94
	v_max_f32_e32 v96, 0xda24260, v96
	v_add_f32_e32 v95, 1.0, v95
	v_rcp_f32_e32 v94, v94
	v_cvt_pk_bf16_f32 v91, v91, v96
	v_rcp_f32_e32 v95, v95
	v_rcp_f32_e32 v96, v92
	v_add_f32_e32 v92, 1.0, v93
	v_rcp_f32_e32 v93, v92
	v_max_f32_e32 v94, 0xda24260, v94
	v_max_f32_e32 v92, 0xda24260, v95
	v_cvt_pk_bf16_f32 v92, v94, v92
	v_max_f32_e32 v94, 0xda24260, v96
	v_max_f32_e32 v93, 0xda24260, v93
	v_cvt_pk_bf16_f32 v93, v94, v93
	v_add_u32_e32 v94, 16, v148
	v_ashrrev_i32_e32 v95, 31, v94
	v_lshlrev_b64 v[94:95], 13, v[94:95]
	v_lshl_add_u64 v[94:95], s[20:21], 0, v[94:95]
	v_lshl_add_u64 v[94:95], v[94:95], 0, s[44:45]
	v_lshl_add_u64 v[94:95], v[94:95], 0, s[16:17]
	v_lshl_add_u64 v[94:95], v[94:95], 0, v[138:139]
	global_store_dwordx4 v[94:95], v[90:93], off
	s_nop 1
	v_mul_f32_e32 v90, 0xbfb8aa3b, v189
; __device__ __forceinline__ unsigned cvt_pk_bf16(float lo, float hi) { f32x2 v = {lo, hi}; bf2_t b = __builtin_convertvector(v, bf2_t); return __builtin_bit_cast(unsigned, b); }
; #define SG_(t) fmaxf(__builtin_amdgcn_rcpf(1.f + __builtin_amdgcn_exp2f(t)), 1e-30f)
;     __device__ __forceinline__ bool operator()(f32x4 (&acc)[2][2][4][2], const Unit& u, int wr, int wc, int fr, int fq) const {
;     ...
;                 const f32x4 nb0 = *(const f32x4*)(bias + gsub * D + colin) * -1.4426950408889634f, nb1 = *(const f32x4*)(bias + gsub * D + colin + 4) * -1.4426950408889634f;
;     ...
;                 for (int ai = 0; ai < 2; ++ai)
; #pragma unroll
;                     for (int m = 0; m < 4; ++m) { const int row = row0 + ai * HALF + m * 16; const float ri = ri8[4 * ai + m];
;                         const float k2 = ri * -1.4426950408889634f;
;                         const f32x4 a = acc[ai][bj][m][0] * k2 + nb0, b = acc[ai][bj][m][1] * k2 + nb1;
;     ...
;                         u32x4 w; w.x = cvt_pk_bf16(SG_(a[0]), SG_(a[1])); w.y = cvt_pk_bf16(SG_(a[2]), SG_(a[3]));
;                         w.z = cvt_pk_bf16(SG_(b[0]), SG_(b[1])); w.w = cvt_pk_bf16(SG_(b[2]), SG_(b[3]));
;     ...
;                         *(u32x4*)gptr(gsub, u.pm, u.pn & 3, wr * 4 + wc, ai * 8 + m * 2 + bj, fq * 16 + fr) = w; } }
	v_pk_fma_f32 v[86:87], v[86:87], v[90:91], v[162:163] op_sel_hi:[1,0,1] neg_lo:[0,0,1] neg_hi:[0,0,1]
	v_pk_fma_f32 v[88:89], v[88:89], v[90:91], v[160:161] op_sel_hi:[1,0,1] neg_lo:[0,0,1] neg_hi:[0,0,1]
	v_exp_f32_e32 v86, v86
	v_exp_f32_e32 v87, v87
	v_pk_fma_f32 v[84:85], v[84:85], v[90:91], v[158:159] op_sel_hi:[1,0,1] neg_lo:[0,0,1] neg_hi:[0,0,1]
	v_add_f32_e32 v86, 1.0, v86
	v_rcp_f32_e32 v91, v86
	v_add_f32_e32 v86, 1.0, v87
	v_rcp_f32_e32 v92, v86
	v_exp_f32_e32 v84, v84
	v_pk_fma_f32 v[86:87], v[82:83], v[90:91], v[156:157] op_sel_hi:[1,0,1] neg_lo:[0,0,1] neg_hi:[0,0,1]
	v_max_f32_e32 v82, 0xda24260, v91
	v_exp_f32_e32 v83, v88
	v_max_f32_e32 v88, 0xda24260, v92
	v_cvt_pk_bf16_f32 v82, v82, v88
	v_exp_f32_e32 v88, v89
	v_add_f32_e32 v83, 1.0, v83
	v_rcp_f32_e32 v83, v83
	v_exp_f32_e32 v86, v86
	v_add_f32_e32 v88, 1.0, v88
	v_rcp_f32_e32 v88, v88
	v_exp_f32_e32 v87, v87
	v_exp_f32_e32 v85, v85
	v_max_f32_e32 v83, 0xda24260, v83
	v_add_f32_e32 v86, 1.0, v86
	v_max_f32_e32 v88, 0xda24260, v88
	v_add_f32_e32 v87, 1.0, v87
	v_add_f32_e32 v84, 1.0, v84
	v_rcp_f32_e32 v86, v86
	v_cvt_pk_bf16_f32 v83, v83, v88
	v_rcp_f32_e32 v87, v87
	v_rcp_f32_e32 v88, v84
	v_add_f32_e32 v84, 1.0, v85
	v_rcp_f32_e32 v85, v84
	v_max_f32_e32 v86, 0xda24260, v86
	v_max_f32_e32 v84, 0xda24260, v87
	v_cvt_pk_bf16_f32 v84, v86, v84
	v_max_f32_e32 v86, 0xda24260, v88
	v_max_f32_e32 v85, 0xda24260, v85
	v_cvt_pk_bf16_f32 v85, v86, v85
	v_add_u32_e32 v86, 20, v148
	v_ashrrev_i32_e32 v87, 31, v86
	v_lshlrev_b64 v[86:87], 13, v[86:87]
	v_lshl_add_u64 v[86:87], s[20:21], 0, v[86:87]
	v_lshl_add_u64 v[86:87], v[86:87], 0, s[44:45]
	v_lshl_add_u64 v[86:87], v[86:87], 0, s[16:17]
	v_lshl_add_u64 v[86:87], v[86:87], 0, v[138:139]
	global_store_dwordx4 v[86:87], v[82:85], off
	s_nop 1
	v_mul_f32_e32 v82, 0xbfb8aa3b, v190
	v_pk_fma_f32 v[78:79], v[78:79], v[82:83], v[162:163] op_sel_hi:[1,0,1] neg_lo:[0,0,1] neg_hi:[0,0,1]
	v_pk_fma_f32 v[80:81], v[80:81], v[82:83], v[160:161] op_sel_hi:[1,0,1] neg_lo:[0,0,1] neg_hi:[0,0,1]
	v_exp_f32_e32 v78, v78
	v_exp_f32_e32 v79, v79
	v_pk_fma_f32 v[76:77], v[76:77], v[82:83], v[158:159] op_sel_hi:[1,0,1] neg_lo:[0,0,1] neg_hi:[0,0,1]
	v_add_f32_e32 v78, 1.0, v78
	v_rcp_f32_e32 v83, v78
	v_add_f32_e32 v78, 1.0, v79
	v_rcp_f32_e32 v84, v78
	v_exp_f32_e32 v76, v76
	v_pk_fma_f32 v[78:79], v[74:75], v[82:83], v[156:157] op_sel_hi:[1,0,1] neg_lo:[0,0,1] neg_hi:[0,0,1]
	v_max_f32_e32 v74, 0xda24260, v83
	v_exp_f32_e32 v75, v80
	v_max_f32_e32 v80, 0xda24260, v84
	v_cvt_pk_bf16_f32 v74, v74, v80
	v_exp_f32_e32 v80, v81
	v_add_f32_e32 v75, 1.0, v75
	v_rcp_f32_e32 v75, v75
	v_exp_f32_e32 v78, v78
	v_add_f32_e32 v80, 1.0, v80
	v_rcp_f32_e32 v80, v80
	v_exp_f32_e32 v79, v79
	v_exp_f32_e32 v77, v77
	v_max_f32_e32 v75, 0xda24260, v75
	v_add_f32_e32 v78, 1.0, v78
	v_max_f32_e32 v80, 0xda24260, v80
	v_add_f32_e32 v79, 1.0, v79
	v_add_f32_e32 v76, 1.0, v76
	v_rcp_f32_e32 v78, v78
	v_cvt_pk_bf16_f32 v75, v75, v80
	v_rcp_f32_e32 v79, v79
	v_rcp_f32_e32 v80, v76
	v_add_f32_e32 v76, 1.0, v77
	v_rcp_f32_e32 v77, v76
	v_max_f32_e32 v78, 0xda24260, v78
	v_max_f32_e32 v76, 0xda24260, v79
	v_cvt_pk_bf16_f32 v76, v78, v76
	v_max_f32_e32 v78, 0xda24260, v80
	v_max_f32_e32 v77, 0xda24260, v77
	v_cvt_pk_bf16_f32 v77, v78, v77
	v_add_u32_e32 v78, 24, v148
	v_ashrrev_i32_e32 v79, 31, v78
	v_lshlrev_b64 v[78:79], 13, v[78:79]
	v_lshl_add_u64 v[78:79], s[20:21], 0, v[78:79]
	v_lshl_add_u64 v[78:79], v[78:79], 0, s[44:45]
	v_lshl_add_u64 v[78:79], v[78:79], 0, s[16:17]
	v_lshl_add_u64 v[78:79], v[78:79], 0, v[138:139]
	global_store_dwordx4 v[78:79], v[74:77], off
	s_nop 1
	v_mul_f32_e32 v74, 0xbfb8aa3b, v149
	v_pk_fma_f32 v[70:71], v[70:71], v[74:75], v[162:163] op_sel_hi:[1,0,1] neg_lo:[0,0,1] neg_hi:[0,0,1]
	v_pk_fma_f32 v[72:73], v[72:73], v[74:75], v[160:161] op_sel_hi:[1,0,1] neg_lo:[0,0,1] neg_hi:[0,0,1]
	v_exp_f32_e32 v70, v70
	v_exp_f32_e32 v71, v71
	v_pk_fma_f32 v[68:69], v[68:69], v[74:75], v[158:159] op_sel_hi:[1,0,1] neg_lo:[0,0,1] neg_hi:[0,0,1]
	v_add_f32_e32 v70, 1.0, v70
	v_rcp_f32_e32 v75, v70
	v_add_f32_e32 v70, 1.0, v71
	v_rcp_f32_e32 v76, v70
	v_exp_f32_e32 v68, v68
	v_pk_fma_f32 v[70:71], v[66:67], v[74:75], v[156:157] op_sel_hi:[1,0,1] neg_lo:[0,0,1] neg_hi:[0,0,1]
	v_max_f32_e32 v66, 0xda24260, v75
	v_exp_f32_e32 v67, v72
	v_max_f32_e32 v72, 0xda24260, v76
	v_cvt_pk_bf16_f32 v66, v66, v72
	v_exp_f32_e32 v72, v73
	v_add_f32_e32 v67, 1.0, v67
	v_rcp_f32_e32 v67, v67
	v_exp_f32_e32 v70, v70
	v_add_f32_e32 v72, 1.0, v72
	v_rcp_f32_e32 v72, v72
	v_exp_f32_e32 v71, v71
	v_exp_f32_e32 v69, v69
	v_max_f32_e32 v67, 0xda24260, v67
	v_add_f32_e32 v70, 1.0, v70
	v_max_f32_e32 v72, 0xda24260, v72
	v_add_f32_e32 v71, 1.0, v71
	v_add_f32_e32 v68, 1.0, v68
	v_rcp_f32_e32 v70, v70
	v_cvt_pk_bf16_f32 v67, v67, v72
	v_rcp_f32_e32 v71, v71
	v_rcp_f32_e32 v72, v68
	v_add_f32_e32 v68, 1.0, v69
	v_rcp_f32_e32 v69, v68
	v_max_f32_e32 v70, 0xda24260, v70
	v_max_f32_e32 v68, 0xda24260, v71
	v_cvt_pk_bf16_f32 v68, v70, v68
	v_max_f32_e32 v70, 0xda24260, v72
	v_max_f32_e32 v69, 0xda24260, v69
	v_cvt_pk_bf16_f32 v69, v70, v69
	v_add_u32_e32 v70, 28, v148
	v_ashrrev_i32_e32 v71, 31, v70
	v_lshlrev_b64 v[70:71], 13, v[70:71]
	v_lshl_add_u64 v[70:71], s[20:21], 0, v[70:71]
	v_lshl_add_u64 v[70:71], v[70:71], 0, s[44:45]
	v_lshl_add_u64 v[70:71], v[70:71], 0, s[16:17]
	v_lshl_add_u64 v[70:71], v[70:71], 0, v[138:139]
	global_store_dwordx4 v[70:71], v[66:69], off
	global_load_dwordx4 v[66:69], v[152:153], off offset:512
	s_nop 0
	global_load_dwordx4 v[76:79], v[152:153], off offset:528
	s_waitcnt vmcnt(1)
; __device__ __forceinline__ unsigned cvt_pk_bf16(float lo, float hi) { f32x2 v = {lo, hi}; bf2_t b = __builtin_convertvector(v, bf2_t); return __builtin_bit_cast(unsigned, b); }
; #define SG_(t) fmaxf(__builtin_amdgcn_rcpf(1.f + __builtin_amdgcn_exp2f(t)), 1e-30f)
;     __device__ __forceinline__ bool operator()(f32x4 (&acc)[2][2][4][2], const Unit& u, int wr, int wc, int fr, int fq) const {
;     ...
;                 const f32x4 nb0 = *(const f32x4*)(bias + gsub * D + colin) * -1.4426950408889634f, nb1 = *(const f32x4*)(bias + gsub * D + colin + 4) * -1.4426950408889634f;
; #pragma unroll
;                 for (int ai = 0; ai < 2; ++ai)
; #pragma unroll
;                     for (int m = 0; m < 4; ++m) { const int row = row0 + ai * HALF + m * 16; const float ri = ri8[4 * ai + m];
;                         const float k2 = ri * -1.4426950408889634f;
;                         const f32x4 a = acc[ai][bj][m][0] * k2 + nb0, b = acc[ai][bj][m][1] * k2 + nb1;
;     ...
;                         u32x4 w; w.x = cvt_pk_bf16(SG_(a[0]), SG_(a[1])); w.y = cvt_pk_bf16(SG_(a[2]), SG_(a[3]));
;                         w.z = cvt_pk_bf16(SG_(b[0]), SG_(b[1])); w.w = cvt_pk_bf16(SG_(b[2]), SG_(b[3]));
;     ...
;                         *(u32x4*)gptr(gsub, u.pm, u.pn & 3, wr * 4 + wc, ai * 8 + m * 2 + bj, fq * 16 + fr) = w; } }
	v_pk_mul_f32 v[72:73], v[66:67], s[26:27] op_sel_hi:[1,0]
	s_nop 0
	v_pk_fma_f32 v[62:63], v[62:63], v[154:155], v[72:73] op_sel_hi:[1,0,1] neg_lo:[0,0,1] neg_hi:[0,0,1]
	s_waitcnt vmcnt(0)
	v_pk_mul_f32 v[66:67], v[76:77], s[26:27] op_sel_hi:[1,0]
	v_exp_f32_e32 v62, v62
	v_exp_f32_e32 v63, v63
	v_pk_mul_f32 v[70:71], v[68:69], s[26:27] op_sel_hi:[1,0]
	v_pk_mul_f32 v[68:69], v[78:79], s[26:27] op_sel_hi:[1,0]
	v_add_f32_e32 v62, 1.0, v62
	v_rcp_f32_e32 v75, v62
	v_add_f32_e32 v62, 1.0, v63
	v_rcp_f32_e32 v76, v62
	v_pk_fma_f32 v[64:65], v[64:65], v[154:155], v[70:71] op_sel_hi:[1,0,1] neg_lo:[0,0,1] neg_hi:[0,0,1]
	v_pk_fma_f32 v[62:63], v[58:59], v[154:155], v[66:67] op_sel_hi:[1,0,1] neg_lo:[0,0,1] neg_hi:[0,0,1]
	v_max_f32_e32 v58, 0xda24260, v75
	v_exp_f32_e32 v59, v64
	v_max_f32_e32 v64, 0xda24260, v76
	v_cvt_pk_bf16_f32 v58, v58, v64
	v_exp_f32_e32 v64, v65
	v_pk_fma_f32 v[60:61], v[60:61], v[154:155], v[68:69] op_sel_hi:[1,0,1] neg_lo:[0,0,1] neg_hi:[0,0,1]
	v_add_f32_e32 v59, 1.0, v59
	v_rcp_f32_e32 v59, v59
	v_add_f32_e32 v64, 1.0, v64
	v_exp_f32_e32 v62, v62
	v_rcp_f32_e32 v64, v64
	v_exp_f32_e32 v63, v63
	v_exp_f32_e32 v60, v60
	v_exp_f32_e32 v61, v61
	v_max_f32_e32 v59, 0xda24260, v59
	v_add_f32_e32 v62, 1.0, v62
	v_max_f32_e32 v64, 0xda24260, v64
	v_add_f32_e32 v63, 1.0, v63
	v_add_f32_e32 v60, 1.0, v60
	v_rcp_f32_e32 v62, v62
	v_cvt_pk_bf16_f32 v59, v59, v64
	v_rcp_f32_e32 v63, v63
	v_rcp_f32_e32 v64, v60
	v_add_f32_e32 v60, 1.0, v61
	v_rcp_f32_e32 v61, v60
	v_max_f32_e32 v62, 0xda24260, v62
	v_max_f32_e32 v60, 0xda24260, v63
	v_cvt_pk_bf16_f32 v60, v62, v60
	v_max_f32_e32 v62, 0xda24260, v64
	v_max_f32_e32 v61, 0xda24260, v61
	v_cvt_pk_bf16_f32 v61, v62, v61
	v_add_u32_e32 v62, 2, v148
	v_ashrrev_i32_e32 v63, 31, v62
	v_pk_fma_f32 v[54:55], v[54:55], v[122:123], v[72:73] op_sel_hi:[1,0,1] neg_lo:[0,0,1] neg_hi:[0,0,1]
	v_lshlrev_b64 v[62:63], 13, v[62:63]
	v_exp_f32_e32 v54, v54
	v_lshl_add_u64 v[62:63], s[20:21], 0, v[62:63]
	v_exp_f32_e32 v55, v55
	v_lshl_add_u64 v[62:63], v[62:63], 0, s[44:45]
	v_lshl_add_u64 v[62:63], v[62:63], 0, s[16:17]
	v_lshl_add_u64 v[62:63], v[62:63], 0, v[138:139]
	v_add_f32_e32 v54, 1.0, v54
	global_store_dwordx4 v[62:63], v[58:61], off
	v_pk_fma_f32 v[56:57], v[56:57], v[122:123], v[70:71] op_sel_hi:[1,0,1] neg_lo:[0,0,1] neg_hi:[0,0,1]
	v_pk_fma_f32 v[52:53], v[52:53], v[122:123], v[68:69] op_sel_hi:[1,0,1] neg_lo:[0,0,1] neg_hi:[0,0,1]
	v_rcp_f32_e32 v58, v54
	v_add_f32_e32 v54, 1.0, v55
	v_rcp_f32_e32 v59, v54
	v_pk_fma_f32 v[54:55], v[50:51], v[122:123], v[66:67] op_sel_hi:[1,0,1] neg_lo:[0,0,1] neg_hi:[0,0,1]
	v_max_f32_e32 v50, 0xda24260, v58
	v_exp_f32_e32 v51, v56
	v_max_f32_e32 v56, 0xda24260, v59
	v_cvt_pk_bf16_f32 v50, v50, v56
	v_exp_f32_e32 v56, v57
	v_add_f32_e32 v51, 1.0, v51
	v_rcp_f32_e32 v51, v51
	v_exp_f32_e32 v54, v54
	v_add_f32_e32 v56, 1.0, v56
	v_rcp_f32_e32 v56, v56
	v_exp_f32_e32 v55, v55
	v_exp_f32_e32 v52, v52
	v_exp_f32_e32 v53, v53
	v_max_f32_e32 v51, 0xda24260, v51
	v_add_f32_e32 v54, 1.0, v54
	v_max_f32_e32 v56, 0xda24260, v56
	v_add_f32_e32 v55, 1.0, v55
	v_add_f32_e32 v52, 1.0, v52
	v_rcp_f32_e32 v54, v54
	v_cvt_pk_bf16_f32 v51, v51, v56
	v_rcp_f32_e32 v55, v55
	v_rcp_f32_e32 v56, v52
	v_add_f32_e32 v52, 1.0, v53
	v_rcp_f32_e32 v53, v52
	v_max_f32_e32 v54, 0xda24260, v54
	v_max_f32_e32 v52, 0xda24260, v55
	v_cvt_pk_bf16_f32 v52, v54, v52
	v_max_f32_e32 v54, 0xda24260, v56
	v_max_f32_e32 v53, 0xda24260, v53
	v_cvt_pk_bf16_f32 v53, v54, v53
	v_add_u32_e32 v54, 6, v148
	v_ashrrev_i32_e32 v55, 31, v54
	v_pk_fma_f32 v[46:47], v[46:47], v[114:115], v[72:73] op_sel_hi:[1,0,1] neg_lo:[0,0,1] neg_hi:[0,0,1]
	v_lshlrev_b64 v[54:55], 13, v[54:55]
	v_exp_f32_e32 v46, v46
	v_lshl_add_u64 v[54:55], s[20:21], 0, v[54:55]
	v_exp_f32_e32 v47, v47
	v_lshl_add_u64 v[54:55], v[54:55], 0, s[44:45]
	v_lshl_add_u64 v[54:55], v[54:55], 0, s[16:17]
	v_lshl_add_u64 v[54:55], v[54:55], 0, v[138:139]
	v_add_f32_e32 v46, 1.0, v46
	global_store_dwordx4 v[54:55], v[50:53], off
	v_pk_fma_f32 v[48:49], v[48:49], v[114:115], v[70:71] op_sel_hi:[1,0,1] neg_lo:[0,0,1] neg_hi:[0,0,1]
	v_pk_fma_f32 v[44:45], v[44:45], v[114:115], v[68:69] op_sel_hi:[1,0,1] neg_lo:[0,0,1] neg_hi:[0,0,1]
	v_rcp_f32_e32 v50, v46
	v_add_f32_e32 v46, 1.0, v47
	v_rcp_f32_e32 v51, v46
	v_pk_fma_f32 v[46:47], v[42:43], v[114:115], v[66:67] op_sel_hi:[1,0,1] neg_lo:[0,0,1] neg_hi:[0,0,1]
	v_max_f32_e32 v42, 0xda24260, v50
	v_exp_f32_e32 v43, v48
	v_max_f32_e32 v48, 0xda24260, v51
	v_cvt_pk_bf16_f32 v42, v42, v48
	v_exp_f32_e32 v48, v49
	v_add_f32_e32 v43, 1.0, v43
	v_rcp_f32_e32 v43, v43
	v_exp_f32_e32 v46, v46
	v_add_f32_e32 v48, 1.0, v48
	v_rcp_f32_e32 v48, v48
	v_exp_f32_e32 v47, v47
	v_exp_f32_e32 v44, v44
	v_exp_f32_e32 v45, v45
	v_max_f32_e32 v43, 0xda24260, v43
	v_add_f32_e32 v46, 1.0, v46
	v_max_f32_e32 v48, 0xda24260, v48
	v_add_f32_e32 v47, 1.0, v47
	v_add_f32_e32 v44, 1.0, v44
	v_rcp_f32_e32 v46, v46
	v_cvt_pk_bf16_f32 v43, v43, v48
	v_rcp_f32_e32 v47, v47
	v_rcp_f32_e32 v48, v44
	v_add_f32_e32 v44, 1.0, v45
	v_rcp_f32_e32 v45, v44
	v_max_f32_e32 v46, 0xda24260, v46
	v_max_f32_e32 v44, 0xda24260, v47
	v_cvt_pk_bf16_f32 v44, v46, v44
	v_max_f32_e32 v46, 0xda24260, v48
	v_max_f32_e32 v45, 0xda24260, v45
	v_cvt_pk_bf16_f32 v45, v46, v45
	v_add_u32_e32 v46, 10, v148
	v_ashrrev_i32_e32 v47, 31, v46
	v_pk_fma_f32 v[38:39], v[38:39], v[106:107], v[72:73] op_sel_hi:[1,0,1] neg_lo:[0,0,1] neg_hi:[0,0,1]
	v_lshlrev_b64 v[46:47], 13, v[46:47]
	v_exp_f32_e32 v38, v38
	v_lshl_add_u64 v[46:47], s[20:21], 0, v[46:47]
	v_exp_f32_e32 v39, v39
	v_lshl_add_u64 v[46:47], v[46:47], 0, s[44:45]
	v_lshl_add_u64 v[46:47], v[46:47], 0, s[16:17]
; __device__ __forceinline__ unsigned cvt_pk_bf16(float lo, float hi) { f32x2 v = {lo, hi}; bf2_t b = __builtin_convertvector(v, bf2_t); return __builtin_bit_cast(unsigned, b); }
; #define SG_(t) fmaxf(__builtin_amdgcn_rcpf(1.f + __builtin_amdgcn_exp2f(t)), 1e-30f)
;     __device__ __forceinline__ bool operator()(f32x4 (&acc)[2][2][4][2], const Unit& u, int wr, int wc, int fr, int fq) const {
;     ...
;                 for (int ai = 0; ai < 2; ++ai)
; #pragma unroll
;                     for (int m = 0; m < 4; ++m) { const int row = row0 + ai * HALF + m * 16; const float ri = ri8[4 * ai + m];
;                         const float k2 = ri * -1.4426950408889634f;
;                         const f32x4 a = acc[ai][bj][m][0] * k2 + nb0, b = acc[ai][bj][m][1] * k2 + nb1;
;     ...
;                         u32x4 w; w.x = cvt_pk_bf16(SG_(a[0]), SG_(a[1])); w.y = cvt_pk_bf16(SG_(a[2]), SG_(a[3]));
;                         w.z = cvt_pk_bf16(SG_(b[0]), SG_(b[1])); w.w = cvt_pk_bf16(SG_(b[2]), SG_(b[3]));
;     ...
;                         *(u32x4*)gptr(gsub, u.pm, u.pn & 3, wr * 4 + wc, ai * 8 + m * 2 + bj, fq * 16 + fr) = w; } }
	v_lshl_add_u64 v[46:47], v[46:47], 0, v[138:139]
	v_add_f32_e32 v38, 1.0, v38
	global_store_dwordx4 v[46:47], v[42:45], off
	v_pk_fma_f32 v[40:41], v[40:41], v[106:107], v[70:71] op_sel_hi:[1,0,1] neg_lo:[0,0,1] neg_hi:[0,0,1]
	v_pk_fma_f32 v[36:37], v[36:37], v[106:107], v[68:69] op_sel_hi:[1,0,1] neg_lo:[0,0,1] neg_hi:[0,0,1]
	v_rcp_f32_e32 v42, v38
	v_add_f32_e32 v38, 1.0, v39
	v_rcp_f32_e32 v43, v38
	v_pk_fma_f32 v[38:39], v[34:35], v[106:107], v[66:67] op_sel_hi:[1,0,1] neg_lo:[0,0,1] neg_hi:[0,0,1]
	v_max_f32_e32 v34, 0xda24260, v42
	v_exp_f32_e32 v35, v40
	v_max_f32_e32 v40, 0xda24260, v43
	v_cvt_pk_bf16_f32 v34, v34, v40
	v_exp_f32_e32 v40, v41
	v_add_f32_e32 v35, 1.0, v35
	v_rcp_f32_e32 v35, v35
	v_exp_f32_e32 v38, v38
	v_add_f32_e32 v40, 1.0, v40
	v_rcp_f32_e32 v40, v40
	v_exp_f32_e32 v39, v39
	v_exp_f32_e32 v36, v36
	v_exp_f32_e32 v37, v37
	v_max_f32_e32 v35, 0xda24260, v35
	v_add_f32_e32 v38, 1.0, v38
	v_max_f32_e32 v40, 0xda24260, v40
	v_add_f32_e32 v39, 1.0, v39
	v_add_f32_e32 v36, 1.0, v36
	v_rcp_f32_e32 v38, v38
	v_cvt_pk_bf16_f32 v35, v35, v40
	v_rcp_f32_e32 v39, v39
	v_rcp_f32_e32 v40, v36
	v_add_f32_e32 v36, 1.0, v37
	v_rcp_f32_e32 v37, v36
	v_max_f32_e32 v38, 0xda24260, v38
	v_max_f32_e32 v36, 0xda24260, v39
	v_cvt_pk_bf16_f32 v36, v38, v36
	v_max_f32_e32 v38, 0xda24260, v40
	v_max_f32_e32 v37, 0xda24260, v37
	v_cvt_pk_bf16_f32 v37, v38, v37
	v_add_u32_e32 v38, 14, v148
	v_ashrrev_i32_e32 v39, 31, v38
	v_pk_fma_f32 v[30:31], v[30:31], v[150:151], v[72:73] op_sel_hi:[1,0,1] neg_lo:[0,0,1] neg_hi:[0,0,1]
	v_lshlrev_b64 v[38:39], 13, v[38:39]
	v_exp_f32_e32 v30, v30
	v_lshl_add_u64 v[38:39], s[20:21], 0, v[38:39]
	v_exp_f32_e32 v31, v31
	v_lshl_add_u64 v[38:39], v[38:39], 0, s[44:45]
	v_lshl_add_u64 v[38:39], v[38:39], 0, s[16:17]
	v_lshl_add_u64 v[38:39], v[38:39], 0, v[138:139]
	v_add_f32_e32 v30, 1.0, v30
	global_store_dwordx4 v[38:39], v[34:37], off
	v_pk_fma_f32 v[32:33], v[32:33], v[150:151], v[70:71] op_sel_hi:[1,0,1] neg_lo:[0,0,1] neg_hi:[0,0,1]
	v_pk_fma_f32 v[28:29], v[28:29], v[150:151], v[68:69] op_sel_hi:[1,0,1] neg_lo:[0,0,1] neg_hi:[0,0,1]
	v_rcp_f32_e32 v34, v30
	v_add_f32_e32 v30, 1.0, v31
	v_rcp_f32_e32 v35, v30
	v_pk_fma_f32 v[30:31], v[26:27], v[150:151], v[66:67] op_sel_hi:[1,0,1] neg_lo:[0,0,1] neg_hi:[0,0,1]
	v_max_f32_e32 v26, 0xda24260, v34
	v_exp_f32_e32 v27, v32
	v_max_f32_e32 v32, 0xda24260, v35
	v_cvt_pk_bf16_f32 v26, v26, v32
	v_exp_f32_e32 v32, v33
	v_add_f32_e32 v27, 1.0, v27
	v_rcp_f32_e32 v27, v27
	v_exp_f32_e32 v30, v30
	v_add_f32_e32 v32, 1.0, v32
	v_rcp_f32_e32 v32, v32
	v_exp_f32_e32 v31, v31
	v_exp_f32_e32 v28, v28
	v_exp_f32_e32 v29, v29
	v_max_f32_e32 v27, 0xda24260, v27
	v_add_f32_e32 v30, 1.0, v30
	v_max_f32_e32 v32, 0xda24260, v32
	v_add_f32_e32 v31, 1.0, v31
	v_add_f32_e32 v28, 1.0, v28
	v_rcp_f32_e32 v30, v30
	v_cvt_pk_bf16_f32 v27, v27, v32
	v_rcp_f32_e32 v31, v31
	v_rcp_f32_e32 v32, v28
	v_add_f32_e32 v28, 1.0, v29
	v_rcp_f32_e32 v29, v28
	v_max_f32_e32 v30, 0xda24260, v30
	v_max_f32_e32 v28, 0xda24260, v31
	v_cvt_pk_bf16_f32 v28, v30, v28
	v_max_f32_e32 v30, 0xda24260, v32
	v_max_f32_e32 v29, 0xda24260, v29
	v_cvt_pk_bf16_f32 v29, v30, v29
	v_add_u32_e32 v30, 18, v148
	v_ashrrev_i32_e32 v31, 31, v30
	v_pk_fma_f32 v[22:23], v[22:23], v[90:91], v[72:73] op_sel_hi:[1,0,1] neg_lo:[0,0,1] neg_hi:[0,0,1]
	v_lshlrev_b64 v[30:31], 13, v[30:31]
	v_exp_f32_e32 v22, v22
	v_lshl_add_u64 v[30:31], s[20:21], 0, v[30:31]
	v_exp_f32_e32 v23, v23
	v_lshl_add_u64 v[30:31], v[30:31], 0, s[44:45]
	v_lshl_add_u64 v[30:31], v[30:31], 0, s[16:17]
	v_lshl_add_u64 v[30:31], v[30:31], 0, v[138:139]
	v_add_f32_e32 v22, 1.0, v22
	global_store_dwordx4 v[30:31], v[26:29], off
	v_pk_fma_f32 v[24:25], v[24:25], v[90:91], v[70:71] op_sel_hi:[1,0,1] neg_lo:[0,0,1] neg_hi:[0,0,1]
	v_pk_fma_f32 v[20:21], v[20:21], v[90:91], v[68:69] op_sel_hi:[1,0,1] neg_lo:[0,0,1] neg_hi:[0,0,1]
	v_rcp_f32_e32 v26, v22
	v_add_f32_e32 v22, 1.0, v23
	v_rcp_f32_e32 v27, v22
	v_pk_fma_f32 v[22:23], v[18:19], v[90:91], v[66:67] op_sel_hi:[1,0,1] neg_lo:[0,0,1] neg_hi:[0,0,1]
	v_max_f32_e32 v18, 0xda24260, v26
	v_exp_f32_e32 v19, v24
	v_max_f32_e32 v24, 0xda24260, v27
	v_cvt_pk_bf16_f32 v18, v18, v24
	v_exp_f32_e32 v24, v25
	v_add_f32_e32 v19, 1.0, v19
	v_rcp_f32_e32 v19, v19
	v_exp_f32_e32 v22, v22
	v_add_f32_e32 v24, 1.0, v24
	v_rcp_f32_e32 v24, v24
	v_exp_f32_e32 v23, v23
	v_exp_f32_e32 v20, v20
	v_exp_f32_e32 v21, v21
; __device__ __forceinline__ unsigned cvt_pk_bf16(float lo, float hi) { f32x2 v = {lo, hi}; bf2_t b = __builtin_convertvector(v, bf2_t); return __builtin_bit_cast(unsigned, b); }
; #define SG_(t) fmaxf(__builtin_amdgcn_rcpf(1.f + __builtin_amdgcn_exp2f(t)), 1e-30f)
; #define PG8_BAR __builtin_amdgcn_s_barrier()
;     __device__ __forceinline__ bool operator()(f32x4 (&acc)[2][2][4][2], const Unit& u, int wr, int wc, int fr, int fq) const {
;     ...
;                 for (int ai = 0; ai < 2; ++ai)
; #pragma unroll
;                     for (int m = 0; m < 4; ++m) { const int row = row0 + ai * HALF + m * 16; const float ri = ri8[4 * ai + m];
;                         const float k2 = ri * -1.4426950408889634f;
;                         const f32x4 a = acc[ai][bj][m][0] * k2 + nb0, b = acc[ai][bj][m][1] * k2 + nb1;
;     ...
;                         u32x4 w; w.x = cvt_pk_bf16(SG_(a[0]), SG_(a[1])); w.y = cvt_pk_bf16(SG_(a[2]), SG_(a[3]));
;                         w.z = cvt_pk_bf16(SG_(b[0]), SG_(b[1])); w.w = cvt_pk_bf16(SG_(b[2]), SG_(b[3]));
;     ...
;                         *(u32x4*)gptr(gsub, u.pm, u.pn & 3, wr * 4 + wc, ai * 8 + m * 2 + bj, fq * 16 + fr) = w; } }
; __device__ __forceinline__ void gemm_phase(LAS unsigned char* lds, const Gemm g, const StaticOrder S, const Epi E) {
;     ...
;         if (nxt.seg == 0) ++ui;
;         cur = nxt; cA = nA; cB = nB;
;         if (wr == 1) PG8_BAR;
	v_max_f32_e32 v19, 0xda24260, v19
	v_add_f32_e32 v22, 1.0, v22
	v_max_f32_e32 v24, 0xda24260, v24
	v_add_f32_e32 v23, 1.0, v23
	v_add_f32_e32 v20, 1.0, v20
	v_rcp_f32_e32 v22, v22
	v_cvt_pk_bf16_f32 v19, v19, v24
	v_rcp_f32_e32 v23, v23
	v_rcp_f32_e32 v24, v20
	v_add_f32_e32 v20, 1.0, v21
	v_rcp_f32_e32 v21, v20
	v_max_f32_e32 v22, 0xda24260, v22
	v_max_f32_e32 v20, 0xda24260, v23
	v_cvt_pk_bf16_f32 v20, v22, v20
	v_max_f32_e32 v22, 0xda24260, v24
	v_max_f32_e32 v21, 0xda24260, v21
	v_cvt_pk_bf16_f32 v21, v22, v21
	v_add_u32_e32 v22, 22, v148
	v_ashrrev_i32_e32 v23, 31, v22
	v_pk_fma_f32 v[14:15], v[14:15], v[82:83], v[72:73] op_sel_hi:[1,0,1] neg_lo:[0,0,1] neg_hi:[0,0,1]
	v_lshlrev_b64 v[22:23], 13, v[22:23]
	v_exp_f32_e32 v14, v14
	v_lshl_add_u64 v[22:23], s[20:21], 0, v[22:23]
	v_exp_f32_e32 v15, v15
	v_lshl_add_u64 v[22:23], v[22:23], 0, s[44:45]
	v_lshl_add_u64 v[22:23], v[22:23], 0, s[16:17]
	v_lshl_add_u64 v[22:23], v[22:23], 0, v[138:139]
	v_add_f32_e32 v14, 1.0, v14
	global_store_dwordx4 v[22:23], v[18:21], off
	v_pk_fma_f32 v[16:17], v[16:17], v[82:83], v[70:71] op_sel_hi:[1,0,1] neg_lo:[0,0,1] neg_hi:[0,0,1]
	v_pk_fma_f32 v[12:13], v[12:13], v[82:83], v[68:69] op_sel_hi:[1,0,1] neg_lo:[0,0,1] neg_hi:[0,0,1]
	v_rcp_f32_e32 v18, v14
	v_add_f32_e32 v14, 1.0, v15
	v_rcp_f32_e32 v19, v14
	v_pk_fma_f32 v[14:15], v[10:11], v[82:83], v[66:67] op_sel_hi:[1,0,1] neg_lo:[0,0,1] neg_hi:[0,0,1]
	v_max_f32_e32 v10, 0xda24260, v18
	v_exp_f32_e32 v11, v16
	v_max_f32_e32 v16, 0xda24260, v19
	v_cvt_pk_bf16_f32 v10, v10, v16
	v_exp_f32_e32 v16, v17
	v_add_f32_e32 v11, 1.0, v11
	v_rcp_f32_e32 v11, v11
	v_exp_f32_e32 v14, v14
	v_add_f32_e32 v16, 1.0, v16
	v_rcp_f32_e32 v16, v16
	v_exp_f32_e32 v15, v15
	v_exp_f32_e32 v12, v12
	v_exp_f32_e32 v13, v13
	v_max_f32_e32 v11, 0xda24260, v11
	v_add_f32_e32 v14, 1.0, v14
	v_max_f32_e32 v16, 0xda24260, v16
	v_add_f32_e32 v15, 1.0, v15
	v_add_f32_e32 v12, 1.0, v12
	v_rcp_f32_e32 v14, v14
	v_cvt_pk_bf16_f32 v11, v11, v16
	v_rcp_f32_e32 v15, v15
	v_rcp_f32_e32 v16, v12
	v_add_f32_e32 v12, 1.0, v13
	v_rcp_f32_e32 v13, v12
	v_max_f32_e32 v14, 0xda24260, v14
	v_max_f32_e32 v12, 0xda24260, v15
	v_cvt_pk_bf16_f32 v12, v14, v12
	v_max_f32_e32 v14, 0xda24260, v16
	v_max_f32_e32 v13, 0xda24260, v13
	v_cvt_pk_bf16_f32 v13, v14, v13
	v_add_u32_e32 v14, 26, v148
	v_ashrrev_i32_e32 v15, 31, v14
	v_pk_fma_f32 v[6:7], v[6:7], v[74:75], v[72:73] op_sel_hi:[1,0,1] neg_lo:[0,0,1] neg_hi:[0,0,1]
	v_lshlrev_b64 v[14:15], 13, v[14:15]
	v_exp_f32_e32 v6, v6
	v_lshl_add_u64 v[14:15], s[20:21], 0, v[14:15]
	v_exp_f32_e32 v7, v7
	v_lshl_add_u64 v[14:15], v[14:15], 0, s[44:45]
	v_lshl_add_u64 v[14:15], v[14:15], 0, s[16:17]
	v_lshl_add_u64 v[14:15], v[14:15], 0, v[138:139]
	v_add_f32_e32 v6, 1.0, v6
	global_store_dwordx4 v[14:15], v[10:13], off
	v_pk_fma_f32 v[8:9], v[8:9], v[74:75], v[70:71] op_sel_hi:[1,0,1] neg_lo:[0,0,1] neg_hi:[0,0,1]
	v_pk_fma_f32 v[4:5], v[4:5], v[74:75], v[68:69] op_sel_hi:[1,0,1] neg_lo:[0,0,1] neg_hi:[0,0,1]
	v_rcp_f32_e32 v10, v6
	v_add_f32_e32 v6, 1.0, v7
	v_rcp_f32_e32 v11, v6
	v_pk_fma_f32 v[6:7], v[2:3], v[74:75], v[66:67] op_sel_hi:[1,0,1] neg_lo:[0,0,1] neg_hi:[0,0,1]
	v_max_f32_e32 v2, 0xda24260, v10
	v_exp_f32_e32 v3, v8
	v_max_f32_e32 v8, 0xda24260, v11
	v_cvt_pk_bf16_f32 v2, v2, v8
	v_exp_f32_e32 v8, v9
	v_add_f32_e32 v3, 1.0, v3
	v_rcp_f32_e32 v3, v3
	v_exp_f32_e32 v6, v6
	v_add_f32_e32 v8, 1.0, v8
	v_rcp_f32_e32 v8, v8
	v_exp_f32_e32 v7, v7
	v_exp_f32_e32 v4, v4
	v_exp_f32_e32 v5, v5
	v_max_f32_e32 v3, 0xda24260, v3
	v_add_f32_e32 v6, 1.0, v6
	v_max_f32_e32 v8, 0xda24260, v8
	v_add_f32_e32 v7, 1.0, v7
	v_add_f32_e32 v4, 1.0, v4
	v_rcp_f32_e32 v6, v6
	v_cvt_pk_bf16_f32 v3, v3, v8
	v_rcp_f32_e32 v7, v7
	v_rcp_f32_e32 v8, v4
	v_add_f32_e32 v4, 1.0, v5
	v_rcp_f32_e32 v5, v4
	v_max_f32_e32 v6, 0xda24260, v6
	v_max_f32_e32 v4, 0xda24260, v7
	v_cvt_pk_bf16_f32 v4, v6, v4
	v_max_f32_e32 v6, 0xda24260, v8
	v_max_f32_e32 v5, 0xda24260, v5
	v_cvt_pk_bf16_f32 v5, v6, v5
	v_add_u32_e32 v6, 30, v148
	v_ashrrev_i32_e32 v7, 31, v6
	v_lshlrev_b64 v[6:7], 13, v[6:7]
	v_lshl_add_u64 v[6:7], s[20:21], 0, v[6:7]
	v_lshl_add_u64 v[6:7], v[6:7], 0, s[44:45]
	v_lshl_add_u64 v[6:7], v[6:7], 0, s[16:17]
	v_lshl_add_u64 v[6:7], v[6:7], 0, v[138:139]
	global_store_dwordx4 v[6:7], v[2:5], off
	s_cbranch_vccnz .LBB0_866
	s_andn2_b64 vcc, exec, s[18:19]
	s_cbranch_vccnz .LBB0_865
	s_barrier
	s_branch .LBB0_865
